# combined: 4-phase GEMM loops with 2/4/4/6 DMA split, loop tail in last load segment, concurrent half epilogues with the extra barrier behind the first epilogue loads
# speedup vs baseline: 1.0040x; 1.0032x over previous
; #define PG8_STAGE(bufoff, gbase, voff) do { _Pragma("unroll") for (int _i = 0; _i < 2; ++_i) \
;         __builtin_amdgcn_global_load_lds((const unsigned*)((const char*)(gbase) + (voff)[_i]), (LAS unsigned*)(lds + (bufoff) + ldsw + _i * 8192), 16, 0, 0); } while (0)
; #define PG8_LDA(dst, b, h) do { _Pragma("unroll") for (int m = 0; m < 4; ++m) _Pragma("unroll") for (int k = 0; k < 2; ++k) dst[m][k] = *(const LAS h16x8*)(lds + PG8_SA(b, h) + aoff + m * 2048 + k * 1024); } while (0)
; #define PG8_LDB(dst, b, h) do { _Pragma("unroll") for (int n = 0; n < 2; ++n) _Pragma("unroll") for (int k = 0; k < 2; ++k) dst[n][k] = *(const LAS h16x8*)(lds + PG8_SB(b, h) + boff + n * 2048 + k * 1024); } while (0)
; #define PG8_MMA(ai, bj, At, Bt_) do { __builtin_amdgcn_s_setprio(1); _Pragma("unroll") for (int m = 0; m < 4; ++m) _Pragma("unroll") for (int n = 0; n < 2; ++n) _Pragma("unroll") for (int k = 0; k < 2; ++k) \
;         acc[ai][bj][m][n] = __builtin_amdgcn_mfma_f32_16x16x32_f16(Bt_[n][k], At[m][k], acc[ai][bj][m][n], 0, 0, 0); __builtin_amdgcn_s_setprio(0); } while (0)
; #define PG8_WAIT_V(n) asm volatile("s_waitcnt vmcnt(" #n ")" ::: "memory")
; #define PG8_WAIT_L(n) asm volatile("s_waitcnt lgkmcnt(" #n ")" ::: "memory")
; template <class Epi, class AMap>
; __device__ __forceinline__ void gemm_phase(LAS unsigned char* lds, const AMap am, const int lda, const h16* Bt, const int ldb, const int M, const int N, const int K, const Epi& E) {
;     ...
;             const bool last = (t == nt - 2);
;             const char* a1 = cA + (size_t)(t + 1) * kstep;
;             const char* a2 = last ? nA : cA + (size_t)(t + 2) * kstep; const char* b2 = last ? nB : cB + (size_t)(t + 2) * kstep;
;             const char* a3 = a2 + kstep; const char* b3 = b2 + kstep;
;             PG8_LDB(B0, 0, 0); PG8_SCHED; PG8_LDA(At, 0, 0); PG8_STAGE(PG8_SA(1, 1), a1 + hstepA, voffA);
;             PG8_WAIT_L(8); PG8_BAR; PG8_WAIT_L(0); PG8_MMA(0, 0, At, B0); PG8_BAR; PG8_SCHED;
;             PG8_LDB(B1, 0, 1); PG8_STAGE(PG8_SB(0, 0), b2, voffB);
;             PG8_BAR; PG8_WAIT_L(0); PG8_MMA(0, 1, At, B1); PG8_BAR;
;             PG8_LDA(At, 0, 1); PG8_STAGE(PG8_SA(0, 0), a2, voffA);
;             PG8_BAR; PG8_WAIT_L(0); PG8_MMA(1, 0, At, B0); PG8_BAR; PG8_SCHED;
;             PG8_STAGE(PG8_SB(0, 1), b2 + hstepB, voffB);
;             PG8_WAIT_V(6); PG8_BAR; PG8_MMA(1, 1, At, B1); PG8_BAR;
.LBB0_61:
	s_add_u32 s26, s22, 0x100
	s_addc_u32 s27, s23, 0
	s_add_i32 s51, 0, 0x10000
	v_add_u32_e32 v144, s51, v147
	ds_read_b128 v[140:143], v144
	ds_read_b128 v[150:153], v144 offset:1024
	ds_read_b128 v[154:157], v144 offset:2048
	ds_read_b128 v[158:161], v144 offset:3072
	s_cmpk_eq_i32 s29, 0x52
	s_cselect_b32 s45, s1, s27
	s_cselect_b32 s44, s0, s26
	s_cselect_b32 s43, s41, s21
	s_cselect_b32 s42, s40, s20
	v_lshl_add_u64 v[144:145], s[22:23], 0, v[136:137]
	s_add_i32 m0, s63, 0xc000
	ds_read_b128 v[162:165], v149
	ds_read_b128 v[166:169], v149 offset:1024
	ds_read_b128 v[170:173], v149 offset:2048
	ds_read_b128 v[174:177], v149 offset:3072
	ds_read_b128 v[178:181], v149 offset:4096
	ds_read_b128 v[182:185], v149 offset:5120
	ds_read_b128 v[186:189], v149 offset:6144
	ds_read_b128 v[190:193], v149 offset:7168
	global_load_lds_dwordx4 v[144:145], off
	v_lshl_add_u64 v[144:145], s[22:23], 0, v[138:139]
	s_add_i32 m0, s63, 0xe000
	s_nop 0
	global_load_lds_dwordx4 v[144:145], off
	s_waitcnt lgkmcnt(11)
	s_add_i32 s60, 0, 0x14000
	v_add_u32_e32 v144, s60, v147
	s_add_i32 s22, s51, s48
	ds_read_b128 v[194:197], v144
	ds_read_b128 v[198:201], v144 offset:1024
	ds_read_b128 v[202:205], v144 offset:2048
	ds_read_b128 v[220:223], v144 offset:3072
	s_waitcnt vmcnt(8) lgkmcnt(0)
	s_barrier
	v_mfma_f32_16x16x32_f16 v[126:129], v[140:143], v[162:165], v[126:129]
	v_mfma_f32_16x16x32_f16 v[122:125], v[154:157], v[162:165], v[122:125]
	v_mfma_f32_16x16x32_f16 v[110:113], v[140:143], v[170:173], v[110:113]
	v_mfma_f32_16x16x32_f16 v[106:109], v[154:157], v[170:173], v[106:109]
	v_mfma_f32_16x16x32_f16 v[94:97], v[140:143], v[178:181], v[94:97]
	v_mfma_f32_16x16x32_f16 v[90:93], v[154:157], v[178:181], v[90:93]
	v_mfma_f32_16x16x32_f16 v[78:81], v[140:143], v[186:189], v[78:81]
	v_mfma_f32_16x16x32_f16 v[74:77], v[154:157], v[186:189], v[74:77]
	v_mfma_f32_16x16x32_f16 v[126:129], v[150:153], v[166:169], v[126:129]
	v_mfma_f32_16x16x32_f16 v[122:125], v[158:161], v[166:169], v[122:125]
	v_mfma_f32_16x16x32_f16 v[110:113], v[150:153], v[174:177], v[110:113]
	v_mfma_f32_16x16x32_f16 v[106:109], v[158:161], v[174:177], v[106:109]
	v_mfma_f32_16x16x32_f16 v[94:97], v[150:153], v[182:185], v[94:97]
	v_mfma_f32_16x16x32_f16 v[90:93], v[158:161], v[182:185], v[90:93]
	v_mfma_f32_16x16x32_f16 v[78:81], v[150:153], v[190:193], v[78:81]
	v_mfma_f32_16x16x32_f16 v[74:77], v[158:161], v[190:193], v[74:77]
	v_mfma_f32_16x16x32_f16 v[118:121], v[194:197], v[162:165], v[118:121]
	v_mfma_f32_16x16x32_f16 v[114:117], v[202:205], v[162:165], v[114:117]
	v_mfma_f32_16x16x32_f16 v[102:105], v[194:197], v[170:173], v[102:105]
	v_mfma_f32_16x16x32_f16 v[98:101], v[202:205], v[170:173], v[98:101]
	v_mfma_f32_16x16x32_f16 v[86:89], v[194:197], v[178:181], v[86:89]
	v_mfma_f32_16x16x32_f16 v[82:85], v[202:205], v[178:181], v[82:85]
	v_mfma_f32_16x16x32_f16 v[70:73], v[194:197], v[186:189], v[70:73]
	v_mfma_f32_16x16x32_f16 v[66:69], v[202:205], v[186:189], v[66:69]
	v_mfma_f32_16x16x32_f16 v[118:121], v[198:201], v[166:169], v[118:121]
	v_mfma_f32_16x16x32_f16 v[114:117], v[220:223], v[166:169], v[114:117]
	v_mfma_f32_16x16x32_f16 v[102:105], v[198:201], v[174:177], v[102:105]
	v_mfma_f32_16x16x32_f16 v[98:101], v[220:223], v[174:177], v[98:101]
	v_mfma_f32_16x16x32_f16 v[86:89], v[198:201], v[182:185], v[86:89]
	v_mfma_f32_16x16x32_f16 v[82:85], v[220:223], v[182:185], v[82:85]
	v_mfma_f32_16x16x32_f16 v[70:73], v[198:201], v[190:193], v[70:73]
	v_mfma_f32_16x16x32_f16 v[66:69], v[220:223], v[190:193], v[66:69]
	s_barrier
	v_lshl_add_u64 v[144:145], s[42:43], 0, v[0:1]
	s_mov_b32 m0, s22
	v_lshl_add_u64 v[206:207], s[42:43], 0, v[134:135]
	global_load_lds_dwordx4 v[144:145], off
	s_add_i32 m0, s22, 0x2000
	s_nop 0
	global_load_lds_dwordx4 v[206:207], off
	s_mov_b32 m0, s63
	v_lshl_add_u64 v[212:213], s[44:45], 0, v[130:131]
	ds_read_b128 v[162:165], v149 offset:16384
	ds_read_b128 v[166:169], v149 offset:17408
	ds_read_b128 v[170:173], v149 offset:18432
	ds_read_b128 v[174:177], v149 offset:19456
	ds_read_b128 v[178:181], v149 offset:20480
	ds_read_b128 v[182:185], v149 offset:21504
	ds_read_b128 v[186:189], v149 offset:22528
	ds_read_b128 v[190:193], v149 offset:23552
	global_load_lds_dwordx4 v[212:213], off
	v_lshl_add_u64 v[214:215], s[44:45], 0, v[132:133]
	s_mov_b32 m0, s64
	s_nop 0
	global_load_lds_dwordx4 v[214:215], off
	s_waitcnt vmcnt(6) lgkmcnt(0)
	s_barrier
	v_mfma_f32_16x16x32_f16 v[62:65], v[140:143], v[162:165], v[62:65]
	v_mfma_f32_16x16x32_f16 v[58:61], v[154:157], v[162:165], v[58:61]
	v_mfma_f32_16x16x32_f16 v[46:49], v[140:143], v[170:173], v[46:49]
	v_mfma_f32_16x16x32_f16 v[42:45], v[154:157], v[170:173], v[42:45]
	v_mfma_f32_16x16x32_f16 v[30:33], v[140:143], v[178:181], v[30:33]
	v_mfma_f32_16x16x32_f16 v[26:29], v[154:157], v[178:181], v[26:29]
	v_mfma_f32_16x16x32_f16 v[14:17], v[140:143], v[186:189], v[14:17]
	v_mfma_f32_16x16x32_f16 v[10:13], v[154:157], v[186:189], v[10:13]
	v_mfma_f32_16x16x32_f16 v[62:65], v[150:153], v[166:169], v[62:65]
	v_mfma_f32_16x16x32_f16 v[58:61], v[158:161], v[166:169], v[58:61]
	v_mfma_f32_16x16x32_f16 v[46:49], v[150:153], v[174:177], v[46:49]
	v_mfma_f32_16x16x32_f16 v[42:45], v[158:161], v[174:177], v[42:45]
	v_mfma_f32_16x16x32_f16 v[30:33], v[150:153], v[182:185], v[30:33]
	v_mfma_f32_16x16x32_f16 v[26:29], v[158:161], v[182:185], v[26:29]
	v_mfma_f32_16x16x32_f16 v[14:17], v[150:153], v[190:193], v[14:17]
	v_mfma_f32_16x16x32_f16 v[10:13], v[158:161], v[190:193], v[10:13]
	v_mfma_f32_16x16x32_f16 v[54:57], v[194:197], v[162:165], v[54:57]
	v_mfma_f32_16x16x32_f16 v[50:53], v[202:205], v[162:165], v[50:53]
	v_mfma_f32_16x16x32_f16 v[38:41], v[194:197], v[170:173], v[38:41]
	v_mfma_f32_16x16x32_f16 v[34:37], v[202:205], v[170:173], v[34:37]
	v_mfma_f32_16x16x32_f16 v[22:25], v[194:197], v[178:181], v[22:25]
	v_mfma_f32_16x16x32_f16 v[18:21], v[202:205], v[178:181], v[18:21]
	v_mfma_f32_16x16x32_f16 v[6:9], v[194:197], v[186:189], v[6:9]
	v_mfma_f32_16x16x32_f16 v[2:5], v[202:205], v[186:189], v[2:5]
	v_mfma_f32_16x16x32_f16 v[54:57], v[198:201], v[166:169], v[54:57]
	v_mfma_f32_16x16x32_f16 v[50:53], v[220:223], v[166:169], v[50:53]
	v_mfma_f32_16x16x32_f16 v[38:41], v[198:201], v[174:177], v[38:41]
	v_mfma_f32_16x16x32_f16 v[34:37], v[220:223], v[174:177], v[34:37]
	v_mfma_f32_16x16x32_f16 v[22:25], v[198:201], v[182:185], v[22:25]
	v_mfma_f32_16x16x32_f16 v[18:21], v[220:223], v[182:185], v[18:21]
	v_mfma_f32_16x16x32_f16 v[6:9], v[198:201], v[190:193], v[6:9]
	v_mfma_f32_16x16x32_f16 v[2:5], v[220:223], v[190:193], v[2:5]
	s_barrier
; #define PG8_STAGE(bufoff, gbase, voff) do { _Pragma("unroll") for (int _i = 0; _i < 2; ++_i) \
;         __builtin_amdgcn_global_load_lds((const unsigned*)((const char*)(gbase) + (voff)[_i]), (LAS unsigned*)(lds + (bufoff) + ldsw + _i * 8192), 16, 0, 0); } while (0)
; #define PG8_LDA(dst, b, h) do { _Pragma("unroll") for (int m = 0; m < 4; ++m) _Pragma("unroll") for (int k = 0; k < 2; ++k) dst[m][k] = *(const LAS h16x8*)(lds + PG8_SA(b, h) + aoff + m * 2048 + k * 1024); } while (0)
; #define PG8_LDB(dst, b, h) do { _Pragma("unroll") for (int n = 0; n < 2; ++n) _Pragma("unroll") for (int k = 0; k < 2; ++k) dst[n][k] = *(const LAS h16x8*)(lds + PG8_SB(b, h) + boff + n * 2048 + k * 1024); } while (0)
; #define PG8_MMA(ai, bj, At, Bt_) do { __builtin_amdgcn_s_setprio(1); _Pragma("unroll") for (int m = 0; m < 4; ++m) _Pragma("unroll") for (int n = 0; n < 2; ++n) _Pragma("unroll") for (int k = 0; k < 2; ++k) \
;         acc[ai][bj][m][n] = __builtin_amdgcn_mfma_f32_16x16x32_f16(Bt_[n][k], At[m][k], acc[ai][bj][m][n], 0, 0, 0); __builtin_amdgcn_s_setprio(0); } while (0)
; #define PG8_WAIT_V(n) asm volatile("s_waitcnt vmcnt(" #n ")" ::: "memory")
; #define PG8_WAIT_L(n) asm volatile("s_waitcnt lgkmcnt(" #n ")" ::: "memory")
; #define PG8_BAR __builtin_amdgcn_s_barrier()
; #define PG8_SCHED __builtin_amdgcn_sched_barrier(0)
; template <class Epi, class AMap>
; __device__ __forceinline__ void gemm_phase(LAS unsigned char* lds, const AMap am, const int lda, const h16* Bt, const int ldb, const int M, const int N, const int K, const Epi& E) {
;     ...
;             PG8_STAGE(PG8_SB(0, 1), b2 + hstepB, voffB);
;             PG8_WAIT_V(6); PG8_BAR; PG8_MMA(1, 1, At, B1); PG8_BAR;
;             PG8_LDB(B0, 1, 0); PG8_SCHED; PG8_LDA(At, 1, 0); PG8_STAGE(PG8_SA(0, 1), a2 + hstepA, voffA);
;             PG8_WAIT_L(8); PG8_BAR; PG8_WAIT_L(0); PG8_MMA(0, 0, At, B0); PG8_BAR; PG8_SCHED;
;             PG8_LDB(B1, 1, 1); PG8_STAGE(PG8_SB(1, 0), b3, voffB);
;             PG8_BAR; PG8_WAIT_L(0); PG8_MMA(0, 1, At, B1); PG8_BAR;
;             PG8_LDA(At, 1, 1); PG8_STAGE(PG8_SA(1, 0), a3, voffA);
;             PG8_BAR; PG8_WAIT_L(0); PG8_MMA(1, 0, At, B0); PG8_BAR; PG8_SCHED;
;             PG8_STAGE(PG8_SB(1, 1), b3 + hstepB, voffB);
;             PG8_WAIT_V(6); PG8_BAR; PG8_MMA(1, 1, At, B1); PG8_BAR;
;         }
	s_add_u32 s22, s42, 0x158000
	s_addc_u32 s23, s43, 0
	s_add_i32 s51, s60, s48
	v_lshl_add_u64 v[232:233], s[22:23], 0, v[0:1]
	s_mov_b32 m0, s51
	s_nop 0
	global_load_lds_dwordx4 v[232:233], off
	v_lshl_add_u64 v[232:233], s[22:23], 0, v[134:135]
	s_add_i32 m0, s51, 0x2000
	s_nop 0
	global_load_lds_dwordx4 v[232:233], off
	s_add_i32 s51, 0, 0x18000
	v_add_u32_e32 v234, s51, v147
	ds_read_b128 v[140:143], v234
	ds_read_b128 v[150:153], v234 offset:1024
	ds_read_b128 v[154:157], v234 offset:2048
	ds_read_b128 v[158:161], v234 offset:3072
	s_add_u32 s22, s44, 0x158000
	s_addc_u32 s23, s45, 0
	s_mov_b32 m0, s65
	v_lshl_add_u64 v[232:233], s[22:23], 0, v[130:131]
	ds_read_b128 v[162:165], v149 offset:32768
	ds_read_b128 v[166:169], v149 offset:33792
	ds_read_b128 v[170:173], v149 offset:34816
	ds_read_b128 v[174:177], v149 offset:35840
	ds_read_b128 v[178:181], v149 offset:36864
	ds_read_b128 v[182:185], v149 offset:37888
	ds_read_b128 v[186:189], v149 offset:38912
	ds_read_b128 v[190:193], v149 offset:39936
	global_load_lds_dwordx4 v[232:233], off
	v_lshl_add_u64 v[232:233], s[22:23], 0, v[132:133]
	s_mov_b32 m0, s68
	s_nop 0
	global_load_lds_dwordx4 v[232:233], off
	s_waitcnt lgkmcnt(11)
	s_add_i32 s44, 0, 0x1c000
	s_add_i32 s22, s51, s48
	v_add_u32_e32 v216, s44, v147
	v_lshl_add_u64 v[144:145], v[144:145], 0, s[92:93]
	s_mov_b32 m0, s22
	ds_read_b128 v[194:197], v216
	ds_read_b128 v[198:201], v216 offset:1024
	ds_read_b128 v[202:205], v216 offset:2048
	ds_read_b128 v[220:223], v216 offset:3072
	s_waitcnt vmcnt(8) lgkmcnt(0)
	s_barrier
	v_mfma_f32_16x16x32_f16 v[126:129], v[140:143], v[162:165], v[126:129]
	v_mfma_f32_16x16x32_f16 v[122:125], v[154:157], v[162:165], v[122:125]
	v_mfma_f32_16x16x32_f16 v[110:113], v[140:143], v[170:173], v[110:113]
	v_mfma_f32_16x16x32_f16 v[106:109], v[154:157], v[170:173], v[106:109]
	v_mfma_f32_16x16x32_f16 v[94:97], v[140:143], v[178:181], v[94:97]
	v_mfma_f32_16x16x32_f16 v[90:93], v[154:157], v[178:181], v[90:93]
	v_mfma_f32_16x16x32_f16 v[78:81], v[140:143], v[186:189], v[78:81]
	v_mfma_f32_16x16x32_f16 v[74:77], v[154:157], v[186:189], v[74:77]
	v_mfma_f32_16x16x32_f16 v[126:129], v[150:153], v[166:169], v[126:129]
	v_mfma_f32_16x16x32_f16 v[122:125], v[158:161], v[166:169], v[122:125]
	v_mfma_f32_16x16x32_f16 v[110:113], v[150:153], v[174:177], v[110:113]
	v_mfma_f32_16x16x32_f16 v[106:109], v[158:161], v[174:177], v[106:109]
	v_mfma_f32_16x16x32_f16 v[94:97], v[150:153], v[182:185], v[94:97]
	v_mfma_f32_16x16x32_f16 v[90:93], v[158:161], v[182:185], v[90:93]
	v_mfma_f32_16x16x32_f16 v[78:81], v[150:153], v[190:193], v[78:81]
	v_mfma_f32_16x16x32_f16 v[74:77], v[158:161], v[190:193], v[74:77]
	v_mfma_f32_16x16x32_f16 v[118:121], v[194:197], v[162:165], v[118:121]
	v_mfma_f32_16x16x32_f16 v[114:117], v[202:205], v[162:165], v[114:117]
	v_mfma_f32_16x16x32_f16 v[102:105], v[194:197], v[170:173], v[102:105]
	v_mfma_f32_16x16x32_f16 v[98:101], v[202:205], v[170:173], v[98:101]
	v_mfma_f32_16x16x32_f16 v[86:89], v[194:197], v[178:181], v[86:89]
	v_mfma_f32_16x16x32_f16 v[82:85], v[202:205], v[178:181], v[82:85]
	v_mfma_f32_16x16x32_f16 v[70:73], v[194:197], v[186:189], v[70:73]
	v_mfma_f32_16x16x32_f16 v[66:69], v[202:205], v[186:189], v[66:69]
	v_mfma_f32_16x16x32_f16 v[118:121], v[198:201], v[166:169], v[118:121]
	v_mfma_f32_16x16x32_f16 v[114:117], v[220:223], v[166:169], v[114:117]
	v_mfma_f32_16x16x32_f16 v[102:105], v[198:201], v[174:177], v[102:105]
	v_mfma_f32_16x16x32_f16 v[98:101], v[220:223], v[174:177], v[98:101]
	v_mfma_f32_16x16x32_f16 v[86:89], v[198:201], v[182:185], v[86:89]
	v_mfma_f32_16x16x32_f16 v[82:85], v[220:223], v[182:185], v[82:85]
	v_mfma_f32_16x16x32_f16 v[70:73], v[198:201], v[190:193], v[70:73]
	v_mfma_f32_16x16x32_f16 v[66:69], v[220:223], v[190:193], v[66:69]
	s_barrier
	global_load_lds_dwordx4 v[144:145], off
	v_lshl_add_u64 v[144:145], v[206:207], 0, s[92:93]
	s_add_i32 m0, s22, 0x2000
	s_nop 0
	global_load_lds_dwordx4 v[144:145], off
	s_mov_b32 m0, s69
	v_lshl_add_u64 v[144:145], v[212:213], 0, s[92:93]
	ds_read_b128 v[162:165], v149 offset:49152
	ds_read_b128 v[166:169], v149 offset:50176
	ds_read_b128 v[170:173], v149 offset:51200
	ds_read_b128 v[174:177], v149 offset:52224
	ds_read_b128 v[178:181], v149 offset:53248
	ds_read_b128 v[182:185], v149 offset:54272
	ds_read_b128 v[186:189], v149 offset:55296
	ds_read_b128 v[190:193], v149 offset:56320
	global_load_lds_dwordx4 v[144:145], off
	v_lshl_add_u64 v[144:145], v[214:215], 0, s[92:93]
	s_mov_b32 m0, s70
	s_nop 0
	global_load_lds_dwordx4 v[144:145], off
	s_add_u32 s22, s42, 0x158080
	s_addc_u32 s23, s43, 0
	s_add_i32 s42, s44, s48
	v_lshl_add_u64 v[232:233], s[22:23], 0, v[0:1]
	s_mov_b32 m0, s42
	s_nop 0
	global_load_lds_dwordx4 v[232:233], off
	v_lshl_add_u64 v[232:233], s[22:23], 0, v[134:135]
	s_add_i32 m0, s42, 0x2000
	s_nop 0
	global_load_lds_dwordx4 v[232:233], off
	s_add_i32 s29, s29, 2
	s_add_u32 s20, s20, 0x100
	s_addc_u32 s21, s21, 0
	s_cmpk_gt_u32 s29, 0x53
	s_mov_b64 s[22:23], s[26:27]
	s_waitcnt vmcnt(8) lgkmcnt(0)
	s_barrier
; #define PG8_STAGE(bufoff, gbase, voff) do { _Pragma("unroll") for (int _i = 0; _i < 2; ++_i) \
;         __builtin_amdgcn_global_load_lds((const unsigned*)((const char*)(gbase) + (voff)[_i]), (LAS unsigned*)(lds + (bufoff) + ldsw + _i * 8192), 16, 0, 0); } while (0)
; #define PG8_MMA(ai, bj, At, Bt_) do { __builtin_amdgcn_s_setprio(1); _Pragma("unroll") for (int m = 0; m < 4; ++m) _Pragma("unroll") for (int n = 0; n < 2; ++n) _Pragma("unroll") for (int k = 0; k < 2; ++k) \
;         acc[ai][bj][m][n] = __builtin_amdgcn_mfma_f32_16x16x32_f16(Bt_[n][k], At[m][k], acc[ai][bj][m][n], 0, 0, 0); __builtin_amdgcn_s_setprio(0); } while (0)
; #define PG8_WAIT_V(n) asm volatile("s_waitcnt vmcnt(" #n ")" ::: "memory")
; #define PG8_WAIT_L(n) asm volatile("s_waitcnt lgkmcnt(" #n ")" ::: "memory")
; #define PG8_BAR __builtin_amdgcn_s_barrier()
; #define PG8_SCHED __builtin_amdgcn_sched_barrier(0)
; template <class Epi, class AMap>
; __device__ __forceinline__ void gemm_phase(LAS unsigned char* lds, const AMap am, const int lda, const h16* Bt, const int ldb, const int M, const int N, const int K, const Epi& E) {
;     ...
;             PG8_BAR; PG8_WAIT_L(0); PG8_MMA(1, 0, At, B0); PG8_BAR; PG8_SCHED;
;             PG8_STAGE(PG8_SB(1, 1), b3 + hstepB, voffB);
;             PG8_WAIT_V(6); PG8_BAR; PG8_MMA(1, 1, At, B1); PG8_BAR;
;         }
;         E(acc, cur, wr, wc, fr, fq);
;     __device__ __forceinline__ void operator()(const f32x4 (&acc)[2][2][4][2], const Unit& u, int wr, int wc, int fr, int fq) const {
;         EPI_ROWS_PERM
; #pragma unroll
;         for (int ai = 0; ai < 2; ++ai)
; #pragma unroll
;             for (int m = 0; m < 4; ++m) { const size_t off = (size_t)(row0 + ai * 128 + m * 16) * DM + colt;
; #pragma unroll
;                 for (int bj = 0; bj < 2; ++bj) {
;                     const h16x8 x = *(const h16x8*)(X + off + bj * 128);
	v_mfma_f32_16x16x32_f16 v[62:65], v[140:143], v[162:165], v[62:65]
	v_mfma_f32_16x16x32_f16 v[58:61], v[154:157], v[162:165], v[58:61]
	v_mfma_f32_16x16x32_f16 v[46:49], v[140:143], v[170:173], v[46:49]
	v_mfma_f32_16x16x32_f16 v[42:45], v[154:157], v[170:173], v[42:45]
	v_mfma_f32_16x16x32_f16 v[30:33], v[140:143], v[178:181], v[30:33]
	v_mfma_f32_16x16x32_f16 v[26:29], v[154:157], v[178:181], v[26:29]
	v_mfma_f32_16x16x32_f16 v[14:17], v[140:143], v[186:189], v[14:17]
	v_mfma_f32_16x16x32_f16 v[10:13], v[154:157], v[186:189], v[10:13]
	v_mfma_f32_16x16x32_f16 v[62:65], v[150:153], v[166:169], v[62:65]
	v_mfma_f32_16x16x32_f16 v[58:61], v[158:161], v[166:169], v[58:61]
	v_mfma_f32_16x16x32_f16 v[46:49], v[150:153], v[174:177], v[46:49]
	v_mfma_f32_16x16x32_f16 v[42:45], v[158:161], v[174:177], v[42:45]
	v_mfma_f32_16x16x32_f16 v[30:33], v[150:153], v[182:185], v[30:33]
	v_mfma_f32_16x16x32_f16 v[26:29], v[158:161], v[182:185], v[26:29]
	v_mfma_f32_16x16x32_f16 v[14:17], v[150:153], v[190:193], v[14:17]
	v_mfma_f32_16x16x32_f16 v[10:13], v[158:161], v[190:193], v[10:13]
	v_mfma_f32_16x16x32_f16 v[54:57], v[194:197], v[162:165], v[54:57]
	v_mfma_f32_16x16x32_f16 v[50:53], v[202:205], v[162:165], v[50:53]
	v_mfma_f32_16x16x32_f16 v[38:41], v[194:197], v[170:173], v[38:41]
	v_mfma_f32_16x16x32_f16 v[34:37], v[202:205], v[170:173], v[34:37]
	v_mfma_f32_16x16x32_f16 v[22:25], v[194:197], v[178:181], v[22:25]
	v_mfma_f32_16x16x32_f16 v[18:21], v[202:205], v[178:181], v[18:21]
	v_mfma_f32_16x16x32_f16 v[6:9], v[194:197], v[186:189], v[6:9]
	v_mfma_f32_16x16x32_f16 v[2:5], v[202:205], v[186:189], v[2:5]
	v_mfma_f32_16x16x32_f16 v[54:57], v[198:201], v[166:169], v[54:57]
	v_mfma_f32_16x16x32_f16 v[50:53], v[220:223], v[166:169], v[50:53]
	v_mfma_f32_16x16x32_f16 v[38:41], v[198:201], v[174:177], v[38:41]
	v_mfma_f32_16x16x32_f16 v[34:37], v[220:223], v[174:177], v[34:37]
	v_mfma_f32_16x16x32_f16 v[22:25], v[198:201], v[182:185], v[22:25]
	v_mfma_f32_16x16x32_f16 v[18:21], v[220:223], v[182:185], v[18:21]
	v_mfma_f32_16x16x32_f16 v[6:9], v[198:201], v[190:193], v[6:9]
	v_mfma_f32_16x16x32_f16 v[2:5], v[220:223], v[190:193], v[2:5]
	s_barrier
	s_cbranch_scc0 .LBB0_61
	v_lshl_add_u32 v144, s35, 8, v146
	v_lshl_or_b32 v142, s50, 8, v148
	v_ashrrev_i32_e32 v145, 31, v144
	v_ashrrev_i32_e32 v143, 31, v142
	v_lshlrev_b64 v[140:141], 11, v[144:145]
	v_lshl_add_u64 v[140:141], v[140:141], 0, v[142:143]
	v_lshlrev_b64 v[140:141], 1, v[140:141]
	v_lshl_add_u64 v[154:155], s[94:95], 0, v[140:141]
	s_mov_b32 s101, 0
	global_load_dwordx4 v[158:161], v[154:155], off
	global_load_dwordx4 v[162:165], v[154:155], off offset:256
	s_mov_b32 s100, 0x10000
	v_lshl_add_u64 v[232:233], v[154:155], 0, s[100:101]
	global_load_dwordx4 v[166:169], v[232:233], off
	global_load_dwordx4 v[170:173], v[232:233], off offset:256
	s_mov_b32 s100, 0x20000
	v_lshl_add_u64 v[232:233], v[154:155], 0, s[100:101]
	global_load_dwordx4 v[174:177], v[232:233], off
	global_load_dwordx4 v[178:181], v[232:233], off offset:256
	s_mov_b32 s100, 0x30000
	v_lshl_add_u64 v[232:233], v[154:155], 0, s[100:101]
	global_load_dwordx4 v[182:185], v[232:233], off
	global_load_dwordx4 v[186:189], v[232:233], off offset:256
	s_mov_b32 s100, 0x80000
	v_lshl_add_u64 v[232:233], v[154:155], 0, s[100:101]
	global_load_dwordx4 v[190:193], v[232:233], off
	global_load_dwordx4 v[194:197], v[232:233], off offset:256
	s_mov_b32 s100, 0x90000
	v_lshl_add_u64 v[232:233], v[154:155], 0, s[100:101]
	global_load_dwordx4 v[198:201], v[232:233], off
	global_load_dwordx4 v[202:205], v[232:233], off offset:256
	s_mov_b32 s100, 0xa0000
	v_lshl_add_u64 v[232:233], v[154:155], 0, s[100:101]
	global_load_dwordx4 v[212:215], v[232:233], off
	global_load_dwordx4 v[220:223], v[232:233], off offset:256
	s_mov_b32 s100, 0xb0000
	v_lshl_add_u64 v[232:233], v[154:155], 0, s[100:101]
	global_load_dwordx4 v[224:227], v[232:233], off
	global_load_dwordx4 v[228:231], v[232:233], off offset:256
	s_mov_b64 s[4:5], 0xb0000
	s_and_b64 vcc, exec, s[38:39]
	s_mov_b32 s50, s72
	s_mov_b64 s[26:27], s[40:41]
	s_mov_b64 s[22:23], s[0:1]
	s_cmpk_gt_u32 s46, 0xff
	s_cbranch_scc1 .Lgx0
	s_barrier

; #define PG8_STAGE(bufoff, gbase, voff) do { _Pragma("unroll") for (int _i = 0; _i < 2; ++_i) \
;         __builtin_amdgcn_global_load_lds((const unsigned*)((const char*)(gbase) + (voff)[_i]), (LAS unsigned*)(lds + (bufoff) + ldsw + _i * 8192), 16, 0, 0); } while (0)
; #define PG8_LDA(dst, b, h) do { _Pragma("unroll") for (int m = 0; m < 4; ++m) _Pragma("unroll") for (int k = 0; k < 2; ++k) dst[m][k] = *(const LAS h16x8*)(lds + PG8_SA(b, h) + aoff + m * 2048 + k * 1024); } while (0)
; #define PG8_LDB(dst, b, h) do { _Pragma("unroll") for (int n = 0; n < 2; ++n) _Pragma("unroll") for (int k = 0; k < 2; ++k) dst[n][k] = *(const LAS h16x8*)(lds + PG8_SB(b, h) + boff + n * 2048 + k * 1024); } while (0)
; #define PG8_MMA(ai, bj, At, Bt_) do { __builtin_amdgcn_s_setprio(1); _Pragma("unroll") for (int m = 0; m < 4; ++m) _Pragma("unroll") for (int n = 0; n < 2; ++n) _Pragma("unroll") for (int k = 0; k < 2; ++k) \
;         acc[ai][bj][m][n] = __builtin_amdgcn_mfma_f32_16x16x32_f16(Bt_[n][k], At[m][k], acc[ai][bj][m][n], 0, 0, 0); __builtin_amdgcn_s_setprio(0); } while (0)
; #define PG8_WAIT_V(n) asm volatile("s_waitcnt vmcnt(" #n ")" ::: "memory")
; #define PG8_WAIT_L(n) asm volatile("s_waitcnt lgkmcnt(" #n ")" ::: "memory")
; template <class Epi, class AMap>
; __device__ __forceinline__ void gemm_phase(LAS unsigned char* lds, const AMap am, const int lda, const h16* Bt, const int ldb, const int M, const int N, const int K, const Epi& E) {
;     ...
;             const bool last = (t == nt - 2);
;             const char* a1 = cA + (size_t)(t + 1) * kstep;
;             const char* a2 = last ? nA : cA + (size_t)(t + 2) * kstep; const char* b2 = last ? nB : cB + (size_t)(t + 2) * kstep;
;             const char* a3 = a2 + kstep; const char* b3 = b2 + kstep;
;             PG8_LDB(B0, 0, 0); PG8_SCHED; PG8_LDA(At, 0, 0); PG8_STAGE(PG8_SA(1, 1), a1 + hstepA, voffA);
;             PG8_WAIT_L(8); PG8_BAR; PG8_WAIT_L(0); PG8_MMA(0, 0, At, B0); PG8_BAR; PG8_SCHED;
;             PG8_LDB(B1, 0, 1); PG8_STAGE(PG8_SB(0, 0), b2, voffB);
;             PG8_BAR; PG8_WAIT_L(0); PG8_MMA(0, 1, At, B1); PG8_BAR;
;             PG8_LDA(At, 0, 1); PG8_STAGE(PG8_SA(0, 0), a2, voffA);
;             PG8_BAR; PG8_WAIT_L(0); PG8_MMA(1, 0, At, B0); PG8_BAR; PG8_SCHED;
;             PG8_STAGE(PG8_SB(0, 1), b2 + hstepB, voffB);
;             PG8_WAIT_V(6); PG8_BAR; PG8_MMA(1, 1, At, B1); PG8_BAR;
.LBB0_92:
	s_add_u32 s0, vcc_lo, 0xfff80080
	s_addc_u32 s1, vcc_hi, -1
	s_add_i32 s67, 0, 0x10000
	v_add_u32_e32 v226, s67, v169
	ds_read_b128 v[66:69], v226
	ds_read_b128 v[70:73], v226 offset:1024
	ds_read_b128 v[74:77], v226 offset:2048
	ds_read_b128 v[78:81], v226 offset:3072
	s_cmp_eq_u32 s60, 28
	s_cselect_b32 s27, s69, s1
	s_cselect_b32 s26, s29, s0
	s_cselect_b32 s49, s73, s66
	s_cselect_b32 s48, s20, s21
	v_lshl_add_u64 v[192:193], vcc, 0, v[172:173]
	s_add_i32 m0, s81, 0xc000
	ds_read_b128 v[90:93], v195
	ds_read_b128 v[94:97], v195 offset:1024
	ds_read_b128 v[98:101], v195 offset:2048
	ds_read_b128 v[102:105], v195 offset:3072
	ds_read_b128 v[176:179], v195 offset:4096
	ds_read_b128 v[180:183], v195 offset:5120
	ds_read_b128 v[184:187], v195 offset:6144
	ds_read_b128 v[188:191], v195 offset:7168
	global_load_lds_dwordx4 v[192:193], off
	v_lshl_add_u64 v[192:193], vcc, 0, v[174:175]
	s_add_i32 m0, s81, 0xe000
	s_nop 0
	global_load_lds_dwordx4 v[192:193], off
	s_waitcnt lgkmcnt(11)
	s_add_i32 s65, 0, 0x14000
	v_add_u32_e32 v192, s65, v169
	s_add_i32 s0, s67, s64
	ds_read_b128 v[196:199], v192
	ds_read_b128 v[200:203], v192 offset:1024
	ds_read_b128 v[204:207], v192 offset:2048
	ds_read_b128 v[220:223], v192 offset:3072
	s_waitcnt vmcnt(8) lgkmcnt(0)
	s_barrier
	v_mfma_f32_16x16x32_f16 v[158:161], v[66:69], v[90:93], v[158:161]
	v_mfma_f32_16x16x32_f16 v[154:157], v[74:77], v[90:93], v[154:157]
	v_mfma_f32_16x16x32_f16 v[142:145], v[66:69], v[98:101], v[142:145]
	v_mfma_f32_16x16x32_f16 v[134:137], v[74:77], v[98:101], v[134:137]
	v_mfma_f32_16x16x32_f16 v[126:129], v[66:69], v[176:179], v[126:129]
	v_mfma_f32_16x16x32_f16 v[118:121], v[74:77], v[176:179], v[118:121]
	v_mfma_f32_16x16x32_f16 v[110:113], v[66:69], v[184:187], v[110:113]
	v_mfma_f32_16x16x32_f16 v[106:109], v[74:77], v[184:187], v[106:109]
	v_mfma_f32_16x16x32_f16 v[158:161], v[70:73], v[94:97], v[158:161]
	v_mfma_f32_16x16x32_f16 v[154:157], v[78:81], v[94:97], v[154:157]
	v_mfma_f32_16x16x32_f16 v[142:145], v[70:73], v[102:105], v[142:145]
	v_mfma_f32_16x16x32_f16 v[134:137], v[78:81], v[102:105], v[134:137]
	v_mfma_f32_16x16x32_f16 v[126:129], v[70:73], v[180:183], v[126:129]
	v_mfma_f32_16x16x32_f16 v[118:121], v[78:81], v[180:183], v[118:121]
	v_mfma_f32_16x16x32_f16 v[110:113], v[70:73], v[188:191], v[110:113]
	v_mfma_f32_16x16x32_f16 v[106:109], v[78:81], v[188:191], v[106:109]
	v_mfma_f32_16x16x32_f16 v[150:153], v[196:199], v[90:93], v[150:153]
	v_mfma_f32_16x16x32_f16 v[146:149], v[204:207], v[90:93], v[146:149]
	v_mfma_f32_16x16x32_f16 v[150:153], v[200:203], v[94:97], v[150:153]
	v_mfma_f32_16x16x32_f16 v[146:149], v[220:223], v[94:97], v[146:149]
	v_mfma_f32_16x16x32_f16 v[138:141], v[196:199], v[98:101], v[138:141]
	v_mfma_f32_16x16x32_f16 v[130:133], v[204:207], v[98:101], v[130:133]
	v_mfma_f32_16x16x32_f16 v[114:117], v[204:207], v[176:179], v[114:117]
	v_mfma_f32_16x16x32_f16 v[86:89], v[196:199], v[184:187], v[86:89]
	v_mfma_f32_16x16x32_f16 v[82:85], v[204:207], v[184:187], v[82:85]
	v_mfma_f32_16x16x32_f16 v[138:141], v[200:203], v[102:105], v[138:141]
	v_mfma_f32_16x16x32_f16 v[130:133], v[220:223], v[102:105], v[130:133]
	v_mfma_f32_16x16x32_f16 v[122:125], v[196:199], v[176:179], v[122:125]
	v_mfma_f32_16x16x32_f16 v[114:117], v[220:223], v[180:183], v[114:117]
	v_mfma_f32_16x16x32_f16 v[86:89], v[200:203], v[188:191], v[86:89]
	v_mfma_f32_16x16x32_f16 v[82:85], v[220:223], v[188:191], v[82:85]
	v_mfma_f32_16x16x32_f16 v[122:125], v[200:203], v[180:183], v[122:125]
	s_barrier
	v_lshl_add_u64 v[192:193], s[48:49], 0, v[0:1]
	s_mov_b32 m0, s0
	v_lshl_add_u64 v[212:213], s[48:49], 0, v[162:163]
	global_load_lds_dwordx4 v[192:193], off
	s_add_i32 m0, s0, 0x2000
	s_nop 0
	global_load_lds_dwordx4 v[212:213], off
	s_mov_b32 m0, s81
	v_lshl_add_u64 v[214:215], s[26:27], 0, v[166:167]
	ds_read_b128 v[90:93], v195 offset:16384
	ds_read_b128 v[94:97], v195 offset:17408
	ds_read_b128 v[98:101], v195 offset:18432
	ds_read_b128 v[102:105], v195 offset:19456
	ds_read_b128 v[176:179], v195 offset:20480
	ds_read_b128 v[180:183], v195 offset:21504
	ds_read_b128 v[184:187], v195 offset:22528
	ds_read_b128 v[188:191], v195 offset:23552
	global_load_lds_dwordx4 v[214:215], off
	v_lshl_add_u64 v[216:217], s[26:27], 0, v[164:165]
	s_mov_b32 m0, s82
	s_nop 0
	global_load_lds_dwordx4 v[216:217], off
	s_waitcnt vmcnt(6) lgkmcnt(0)
	s_barrier
	v_mfma_f32_16x16x32_f16 v[62:65], v[66:69], v[90:93], v[62:65]
	v_mfma_f32_16x16x32_f16 v[58:61], v[74:77], v[90:93], v[58:61]
	v_mfma_f32_16x16x32_f16 v[46:49], v[66:69], v[98:101], v[46:49]
	v_mfma_f32_16x16x32_f16 v[38:41], v[74:77], v[98:101], v[38:41]
	v_mfma_f32_16x16x32_f16 v[30:33], v[66:69], v[176:179], v[30:33]
	v_mfma_f32_16x16x32_f16 v[22:25], v[74:77], v[176:179], v[22:25]
	v_mfma_f32_16x16x32_f16 v[14:17], v[66:69], v[184:187], v[14:17]
	v_mfma_f32_16x16x32_f16 v[10:13], v[74:77], v[184:187], v[10:13]
	v_mfma_f32_16x16x32_f16 v[62:65], v[70:73], v[94:97], v[62:65]
	v_mfma_f32_16x16x32_f16 v[58:61], v[78:81], v[94:97], v[58:61]
	v_mfma_f32_16x16x32_f16 v[46:49], v[70:73], v[102:105], v[46:49]
	v_mfma_f32_16x16x32_f16 v[38:41], v[78:81], v[102:105], v[38:41]
	v_mfma_f32_16x16x32_f16 v[30:33], v[70:73], v[180:183], v[30:33]
	v_mfma_f32_16x16x32_f16 v[22:25], v[78:81], v[180:183], v[22:25]
	v_mfma_f32_16x16x32_f16 v[14:17], v[70:73], v[188:191], v[14:17]
	v_mfma_f32_16x16x32_f16 v[10:13], v[78:81], v[188:191], v[10:13]
	v_mfma_f32_16x16x32_f16 v[54:57], v[196:199], v[90:93], v[54:57]
	v_mfma_f32_16x16x32_f16 v[50:53], v[204:207], v[90:93], v[50:53]
	v_mfma_f32_16x16x32_f16 v[42:45], v[196:199], v[98:101], v[42:45]
	v_mfma_f32_16x16x32_f16 v[34:37], v[204:207], v[98:101], v[34:37]
	v_mfma_f32_16x16x32_f16 v[26:29], v[196:199], v[176:179], v[26:29]
	v_mfma_f32_16x16x32_f16 v[18:21], v[204:207], v[176:179], v[18:21]
	v_mfma_f32_16x16x32_f16 v[6:9], v[196:199], v[184:187], v[6:9]
	v_mfma_f32_16x16x32_f16 v[2:5], v[204:207], v[184:187], v[2:5]
	v_mfma_f32_16x16x32_f16 v[54:57], v[200:203], v[94:97], v[54:57]
	v_mfma_f32_16x16x32_f16 v[50:53], v[220:223], v[94:97], v[50:53]
	v_mfma_f32_16x16x32_f16 v[42:45], v[200:203], v[102:105], v[42:45]
	v_mfma_f32_16x16x32_f16 v[34:37], v[220:223], v[102:105], v[34:37]
	v_mfma_f32_16x16x32_f16 v[26:29], v[200:203], v[180:183], v[26:29]
	v_mfma_f32_16x16x32_f16 v[18:21], v[220:223], v[180:183], v[18:21]
	v_mfma_f32_16x16x32_f16 v[6:9], v[200:203], v[188:191], v[6:9]
	v_mfma_f32_16x16x32_f16 v[2:5], v[220:223], v[188:191], v[2:5]
	s_barrier
; #define PG8_STAGE(bufoff, gbase, voff) do { _Pragma("unroll") for (int _i = 0; _i < 2; ++_i) \
;         __builtin_amdgcn_global_load_lds((const unsigned*)((const char*)(gbase) + (voff)[_i]), (LAS unsigned*)(lds + (bufoff) + ldsw + _i * 8192), 16, 0, 0); } while (0)
; #define PG8_LDA(dst, b, h) do { _Pragma("unroll") for (int m = 0; m < 4; ++m) _Pragma("unroll") for (int k = 0; k < 2; ++k) dst[m][k] = *(const LAS h16x8*)(lds + PG8_SA(b, h) + aoff + m * 2048 + k * 1024); } while (0)
; #define PG8_LDB(dst, b, h) do { _Pragma("unroll") for (int n = 0; n < 2; ++n) _Pragma("unroll") for (int k = 0; k < 2; ++k) dst[n][k] = *(const LAS h16x8*)(lds + PG8_SB(b, h) + boff + n * 2048 + k * 1024); } while (0)
; #define PG8_MMA(ai, bj, At, Bt_) do { __builtin_amdgcn_s_setprio(1); _Pragma("unroll") for (int m = 0; m < 4; ++m) _Pragma("unroll") for (int n = 0; n < 2; ++n) _Pragma("unroll") for (int k = 0; k < 2; ++k) \
;         acc[ai][bj][m][n] = __builtin_amdgcn_mfma_f32_16x16x32_f16(Bt_[n][k], At[m][k], acc[ai][bj][m][n], 0, 0, 0); __builtin_amdgcn_s_setprio(0); } while (0)
; #define PG8_WAIT_V(n) asm volatile("s_waitcnt vmcnt(" #n ")" ::: "memory")
; #define PG8_WAIT_L(n) asm volatile("s_waitcnt lgkmcnt(" #n ")" ::: "memory")
; #define PG8_BAR __builtin_amdgcn_s_barrier()
; #define PG8_SCHED __builtin_amdgcn_sched_barrier(0)
; template <class Epi, class AMap>
; __device__ __forceinline__ void gemm_phase(LAS unsigned char* lds, const AMap am, const int lda, const h16* Bt, const int ldb, const int M, const int N, const int K, const Epi& E) {
;     ...
;             PG8_STAGE(PG8_SB(0, 1), b2 + hstepB, voffB);
;             PG8_WAIT_V(6); PG8_BAR; PG8_MMA(1, 1, At, B1); PG8_BAR;
;             PG8_LDB(B0, 1, 0); PG8_SCHED; PG8_LDA(At, 1, 0); PG8_STAGE(PG8_SA(0, 1), a2 + hstepA, voffA);
;             PG8_WAIT_L(8); PG8_BAR; PG8_WAIT_L(0); PG8_MMA(0, 0, At, B0); PG8_BAR; PG8_SCHED;
;             PG8_LDB(B1, 1, 1); PG8_STAGE(PG8_SB(1, 0), b3, voffB);
;             PG8_BAR; PG8_WAIT_L(0); PG8_MMA(0, 1, At, B1); PG8_BAR;
	s_add_u32 s0, s48, 0x80000
	s_addc_u32 s1, s49, 0
	s_add_i32 s65, s65, s64
	v_lshl_add_u64 v[224:225], s[0:1], 0, v[0:1]
	s_mov_b32 m0, s65
	s_nop 0
	global_load_lds_dwordx4 v[224:225], off
	v_lshl_add_u64 v[224:225], s[0:1], 0, v[162:163]
	s_add_i32 m0, s65, 0x2000
	s_nop 0
	global_load_lds_dwordx4 v[224:225], off
	s_add_i32 s65, 0, 0x18000
	v_add_u32_e32 v226, s65, v169
	ds_read_b128 v[66:69], v226
	ds_read_b128 v[70:73], v226 offset:1024
	ds_read_b128 v[74:77], v226 offset:2048
	ds_read_b128 v[78:81], v226 offset:3072
	s_add_u32 s0, s26, 0x80000
	s_addc_u32 s1, s27, 0
	s_mov_b32 m0, s83
	v_lshl_add_u64 v[224:225], s[0:1], 0, v[166:167]
	ds_read_b128 v[90:93], v195 offset:32768
	ds_read_b128 v[94:97], v195 offset:33792
	ds_read_b128 v[98:101], v195 offset:34816
	ds_read_b128 v[102:105], v195 offset:35840
	ds_read_b128 v[176:179], v195 offset:36864
	ds_read_b128 v[180:183], v195 offset:37888
	ds_read_b128 v[184:187], v195 offset:38912
	ds_read_b128 v[188:191], v195 offset:39936
	global_load_lds_dwordx4 v[224:225], off
	v_lshl_add_u64 v[224:225], s[0:1], 0, v[164:165]
	s_mov_b32 m0, s50
	s_nop 0
	global_load_lds_dwordx4 v[224:225], off
	s_waitcnt lgkmcnt(11)
	s_add_i32 s26, 0, 0x1c000
	v_add_u32_e32 v226, s26, v169
	s_add_i32 s0, s65, s64
	ds_read_b128 v[196:199], v226
	ds_read_b128 v[200:203], v226 offset:1024
	ds_read_b128 v[204:207], v226 offset:2048
	ds_read_b128 v[220:223], v226 offset:3072
	s_waitcnt vmcnt(8) lgkmcnt(0)
	s_barrier
	v_mfma_f32_16x16x32_f16 v[158:161], v[66:69], v[90:93], v[158:161]
	v_mfma_f32_16x16x32_f16 v[158:161], v[70:73], v[94:97], v[158:161]
	v_mfma_f32_16x16x32_f16 v[154:157], v[74:77], v[90:93], v[154:157]
	v_mfma_f32_16x16x32_f16 v[154:157], v[78:81], v[94:97], v[154:157]
	v_mfma_f32_16x16x32_f16 v[142:145], v[66:69], v[98:101], v[142:145]
	v_mfma_f32_16x16x32_f16 v[134:137], v[74:77], v[98:101], v[134:137]
	v_mfma_f32_16x16x32_f16 v[126:129], v[66:69], v[176:179], v[126:129]
	v_mfma_f32_16x16x32_f16 v[118:121], v[74:77], v[176:179], v[118:121]
	v_mfma_f32_16x16x32_f16 v[110:113], v[66:69], v[184:187], v[110:113]
	v_mfma_f32_16x16x32_f16 v[106:109], v[74:77], v[184:187], v[106:109]
	v_mfma_f32_16x16x32_f16 v[142:145], v[70:73], v[102:105], v[142:145]
	v_mfma_f32_16x16x32_f16 v[134:137], v[78:81], v[102:105], v[134:137]
	v_mfma_f32_16x16x32_f16 v[126:129], v[70:73], v[180:183], v[126:129]
	v_mfma_f32_16x16x32_f16 v[118:121], v[78:81], v[180:183], v[118:121]
	v_mfma_f32_16x16x32_f16 v[110:113], v[70:73], v[188:191], v[110:113]
	v_mfma_f32_16x16x32_f16 v[106:109], v[78:81], v[188:191], v[106:109]
	v_mfma_f32_16x16x32_f16 v[146:149], v[204:207], v[90:93], v[146:149]
	v_mfma_f32_16x16x32_f16 v[150:153], v[196:199], v[90:93], v[150:153]
	v_mfma_f32_16x16x32_f16 v[146:149], v[220:223], v[94:97], v[146:149]
	v_mfma_f32_16x16x32_f16 v[138:141], v[196:199], v[98:101], v[138:141]
	v_mfma_f32_16x16x32_f16 v[150:153], v[200:203], v[94:97], v[150:153]
	v_mfma_f32_16x16x32_f16 v[138:141], v[200:203], v[102:105], v[138:141]
	v_mfma_f32_16x16x32_f16 v[130:133], v[204:207], v[98:101], v[130:133]
	v_mfma_f32_16x16x32_f16 v[130:133], v[220:223], v[102:105], v[130:133]
	v_mfma_f32_16x16x32_f16 v[122:125], v[196:199], v[176:179], v[122:125]
	v_mfma_f32_16x16x32_f16 v[122:125], v[200:203], v[180:183], v[122:125]
	v_mfma_f32_16x16x32_f16 v[114:117], v[204:207], v[176:179], v[114:117]
	v_mfma_f32_16x16x32_f16 v[86:89], v[196:199], v[184:187], v[86:89]
	v_mfma_f32_16x16x32_f16 v[82:85], v[204:207], v[184:187], v[82:85]
	v_mfma_f32_16x16x32_f16 v[114:117], v[220:223], v[180:183], v[114:117]
	v_mfma_f32_16x16x32_f16 v[86:89], v[200:203], v[188:191], v[86:89]
	v_mfma_f32_16x16x32_f16 v[82:85], v[220:223], v[188:191], v[82:85]
	s_barrier
; #define PG8_STAGE(bufoff, gbase, voff) do { _Pragma("unroll") for (int _i = 0; _i < 2; ++_i) \
;         __builtin_amdgcn_global_load_lds((const unsigned*)((const char*)(gbase) + (voff)[_i]), (LAS unsigned*)(lds + (bufoff) + ldsw + _i * 8192), 16, 0, 0); } while (0)
; #define PG8_LDA(dst, b, h) do { _Pragma("unroll") for (int m = 0; m < 4; ++m) _Pragma("unroll") for (int k = 0; k < 2; ++k) dst[m][k] = *(const LAS h16x8*)(lds + PG8_SA(b, h) + aoff + m * 2048 + k * 1024); } while (0)
; #define PG8_MMA(ai, bj, At, Bt_) do { __builtin_amdgcn_s_setprio(1); _Pragma("unroll") for (int m = 0; m < 4; ++m) _Pragma("unroll") for (int n = 0; n < 2; ++n) _Pragma("unroll") for (int k = 0; k < 2; ++k) \
;         acc[ai][bj][m][n] = __builtin_amdgcn_mfma_f32_16x16x32_f16(Bt_[n][k], At[m][k], acc[ai][bj][m][n], 0, 0, 0); __builtin_amdgcn_s_setprio(0); } while (0)
; #define PG8_WAIT_V(n) asm volatile("s_waitcnt vmcnt(" #n ")" ::: "memory")
; #define PG8_WAIT_L(n) asm volatile("s_waitcnt lgkmcnt(" #n ")" ::: "memory")
; #define PG8_BAR __builtin_amdgcn_s_barrier()
; #define PG8_SCHED __builtin_amdgcn_sched_barrier(0)
; template <class Epi, class AMap>
; __device__ __forceinline__ void gemm_phase(LAS unsigned char* lds, const AMap am, const int lda, const h16* Bt, const int ldb, const int M, const int N, const int K, const Epi& E) {
;     ...
;             PG8_LDA(At, 1, 1); PG8_STAGE(PG8_SA(1, 0), a3, voffA);
;             PG8_BAR; PG8_WAIT_L(0); PG8_MMA(1, 0, At, B0); PG8_BAR; PG8_SCHED;
;             PG8_STAGE(PG8_SB(1, 1), b3 + hstepB, voffB);
;             PG8_WAIT_V(6); PG8_BAR; PG8_MMA(1, 1, At, B1); PG8_BAR;
;         }
;         E(acc, cur, wr, wc, fr, fq);
;     __device__ __forceinline__ void operator()(const f32x4 (&acc)[2][2][4][2], const Unit& u, int wr, int wc, int fr, int fq) const {
;         const int row0 = u.pm * 256 + wr * 64 + fr, f0 = u.pn * 128 + wc * 32 + 8 * fq;
;         f32x4 w0[2], w1[2], w2[2], bb[2];
; #pragma unroll
;         for (int n = 0; n < 2; ++n) { w0[n] = *(const f32x4*)(cw + f0 + 4 * n); w1[n] = *(const f32x4*)(cw + FF + f0 + 4 * n); w2[n] = *(const f32x4*)(cw + 2 * FF + f0 + 4 * n); bb[n] = *(const f32x4*)(cb + f0 + 4 * n); }
	v_lshl_add_u64 v[224:225], v[192:193], 0, s[92:93]
	s_mov_b32 m0, s0
	s_nop 0
	global_load_lds_dwordx4 v[224:225], off
	v_lshl_add_u64 v[224:225], v[212:213], 0, s[92:93]
	s_add_i32 m0, s0, 0x2000
	s_nop 0
	global_load_lds_dwordx4 v[224:225], off
	s_mov_b32 m0, s89
	v_lshl_add_u64 v[192:193], v[214:215], 0, s[92:93]
	ds_read_b128 v[90:93], v195 offset:49152
	ds_read_b128 v[94:97], v195 offset:50176
	ds_read_b128 v[98:101], v195 offset:51200
	ds_read_b128 v[102:105], v195 offset:52224
	ds_read_b128 v[176:179], v195 offset:53248
	ds_read_b128 v[180:183], v195 offset:54272
	ds_read_b128 v[184:187], v195 offset:55296
	ds_read_b128 v[188:191], v195 offset:56320
	global_load_lds_dwordx4 v[192:193], off
	v_lshl_add_u64 v[192:193], v[216:217], 0, s[92:93]
	s_mov_b32 m0, s35
	s_nop 0
	global_load_lds_dwordx4 v[192:193], off
	s_add_u32 s0, s48, 0x80080
	s_addc_u32 s1, s49, 0
	s_add_i32 s26, s26, s64
	v_lshl_add_u64 v[224:225], s[0:1], 0, v[0:1]
	s_mov_b32 m0, s26
	s_nop 0
	global_load_lds_dwordx4 v[224:225], off
	v_lshl_add_u64 v[224:225], s[0:1], 0, v[162:163]
	s_add_i32 m0, s26, 0x2000
	s_nop 0
	global_load_lds_dwordx4 v[224:225], off
	s_add_i32 s60, s60, 2
	s_add_u32 vcc_lo, vcc_lo, 0x100
	s_addc_u32 vcc_hi, vcc_hi, 0
	s_add_u32 s21, s21, 0x100
	s_addc_u32 s66, s66, 0
	s_cmp_gt_u32 s60, 29
	s_waitcnt vmcnt(8) lgkmcnt(0)
	s_barrier
	v_mfma_f32_16x16x32_f16 v[62:65], v[66:69], v[90:93], v[62:65]
	v_mfma_f32_16x16x32_f16 v[58:61], v[74:77], v[90:93], v[58:61]
	v_mfma_f32_16x16x32_f16 v[46:49], v[66:69], v[98:101], v[46:49]
	v_mfma_f32_16x16x32_f16 v[38:41], v[74:77], v[98:101], v[38:41]
	v_mfma_f32_16x16x32_f16 v[30:33], v[66:69], v[176:179], v[30:33]
	v_mfma_f32_16x16x32_f16 v[22:25], v[74:77], v[176:179], v[22:25]
	v_mfma_f32_16x16x32_f16 v[14:17], v[66:69], v[184:187], v[14:17]
	v_mfma_f32_16x16x32_f16 v[10:13], v[74:77], v[184:187], v[10:13]
	v_mfma_f32_16x16x32_f16 v[62:65], v[70:73], v[94:97], v[62:65]
	v_mfma_f32_16x16x32_f16 v[58:61], v[78:81], v[94:97], v[58:61]
	v_mfma_f32_16x16x32_f16 v[46:49], v[70:73], v[102:105], v[46:49]
	v_mfma_f32_16x16x32_f16 v[38:41], v[78:81], v[102:105], v[38:41]
	v_mfma_f32_16x16x32_f16 v[30:33], v[70:73], v[180:183], v[30:33]
	v_mfma_f32_16x16x32_f16 v[22:25], v[78:81], v[180:183], v[22:25]
	v_mfma_f32_16x16x32_f16 v[14:17], v[70:73], v[188:191], v[14:17]
	v_mfma_f32_16x16x32_f16 v[10:13], v[78:81], v[188:191], v[10:13]
	v_mfma_f32_16x16x32_f16 v[54:57], v[196:199], v[90:93], v[54:57]
	v_mfma_f32_16x16x32_f16 v[50:53], v[204:207], v[90:93], v[50:53]
	v_mfma_f32_16x16x32_f16 v[42:45], v[196:199], v[98:101], v[42:45]
	v_mfma_f32_16x16x32_f16 v[34:37], v[204:207], v[98:101], v[34:37]
	v_mfma_f32_16x16x32_f16 v[26:29], v[196:199], v[176:179], v[26:29]
	v_mfma_f32_16x16x32_f16 v[18:21], v[204:207], v[176:179], v[18:21]
	v_mfma_f32_16x16x32_f16 v[6:9], v[196:199], v[184:187], v[6:9]
	v_mfma_f32_16x16x32_f16 v[2:5], v[204:207], v[184:187], v[2:5]
	v_mfma_f32_16x16x32_f16 v[54:57], v[200:203], v[94:97], v[54:57]
	v_mfma_f32_16x16x32_f16 v[50:53], v[220:223], v[94:97], v[50:53]
	v_mfma_f32_16x16x32_f16 v[42:45], v[200:203], v[102:105], v[42:45]
	v_mfma_f32_16x16x32_f16 v[34:37], v[220:223], v[102:105], v[34:37]
	v_mfma_f32_16x16x32_f16 v[26:29], v[200:203], v[180:183], v[26:29]
	v_mfma_f32_16x16x32_f16 v[18:21], v[220:223], v[180:183], v[18:21]
	v_mfma_f32_16x16x32_f16 v[6:9], v[200:203], v[188:191], v[6:9]
	v_mfma_f32_16x16x32_f16 v[2:5], v[220:223], v[188:191], v[2:5]
	s_barrier
	s_cbranch_scc0 .LBB0_92
	v_lshl_or_b32 v176, s23, 7, v194
	v_ashrrev_i32_e32 v177, 31, v176
	v_lshlrev_b64 v[66:67], 2, v[176:177]
	v_lshl_add_u64 v[70:71], s[74:75], 0, v[66:67]
	v_lshl_add_u64 v[74:75], s[8:9], 0, v[66:67]
	v_lshl_add_u64 v[78:79], s[70:71], 0, v[66:67]
	v_lshl_add_u64 v[102:103], s[78:79], 0, v[66:67]
	global_load_dwordx4 v[66:69], v[70:71], off offset:16
	global_load_dwordx4 v[90:93], v[70:71], off
	s_nop 0
	global_load_dwordx4 v[70:73], v[74:75], off offset:16
	global_load_dwordx4 v[94:97], v[74:75], off
	s_nop 0
	global_load_dwordx4 v[74:77], v[78:79], off offset:16
	global_load_dwordx4 v[98:101], v[78:79], off
	s_nop 0
	global_load_dwordx4 v[78:81], v[102:103], off offset:16
	s_nop 0
	global_load_dwordx4 v[102:105], v[102:103], off
	s_cmpk_gt_u32 s10, 0xff
	s_cbranch_scc1 .Lgx1
	s_barrier

; #define PG8_STAGE(bufoff, gbase, voff) do { _Pragma("unroll") for (int _i = 0; _i < 2; ++_i) \
;         __builtin_amdgcn_global_load_lds((const unsigned*)((const char*)(gbase) + (voff)[_i]), (LAS unsigned*)(lds + (bufoff) + ldsw + _i * 8192), 16, 0, 0); } while (0)
; #define PG8_LDA(dst, b, h) do { _Pragma("unroll") for (int m = 0; m < 4; ++m) _Pragma("unroll") for (int k = 0; k < 2; ++k) dst[m][k] = *(const LAS h16x8*)(lds + PG8_SA(b, h) + aoff + m * 2048 + k * 1024); } while (0)
; #define PG8_LDB(dst, b, h) do { _Pragma("unroll") for (int n = 0; n < 2; ++n) _Pragma("unroll") for (int k = 0; k < 2; ++k) dst[n][k] = *(const LAS h16x8*)(lds + PG8_SB(b, h) + boff + n * 2048 + k * 1024); } while (0)
; #define PG8_MMA(ai, bj, At, Bt_) do { __builtin_amdgcn_s_setprio(1); _Pragma("unroll") for (int m = 0; m < 4; ++m) _Pragma("unroll") for (int n = 0; n < 2; ++n) _Pragma("unroll") for (int k = 0; k < 2; ++k) \
;         acc[ai][bj][m][n] = __builtin_amdgcn_mfma_f32_16x16x32_f16(Bt_[n][k], At[m][k], acc[ai][bj][m][n], 0, 0, 0); __builtin_amdgcn_s_setprio(0); } while (0)
; #define PG8_WAIT_V(n) asm volatile("s_waitcnt vmcnt(" #n ")" ::: "memory")
; #define PG8_WAIT_L(n) asm volatile("s_waitcnt lgkmcnt(" #n ")" ::: "memory")
; template <class Epi, class AMap>
; __device__ __forceinline__ void gemm_phase(LAS unsigned char* lds, const AMap am, const int lda, const h16* Bt, const int ldb, const int M, const int N, const int K, const Epi& E) {
;     ...
;             const bool last = (t == nt - 2);
;             const char* a1 = cA + (size_t)(t + 1) * kstep;
;             const char* a2 = last ? nA : cA + (size_t)(t + 2) * kstep; const char* b2 = last ? nB : cB + (size_t)(t + 2) * kstep;
;             const char* a3 = a2 + kstep; const char* b3 = b2 + kstep;
;             PG8_LDB(B0, 0, 0); PG8_SCHED; PG8_LDA(At, 0, 0); PG8_STAGE(PG8_SA(1, 1), a1 + hstepA, voffA);
;             PG8_WAIT_L(8); PG8_BAR; PG8_WAIT_L(0); PG8_MMA(0, 0, At, B0); PG8_BAR; PG8_SCHED;
;             PG8_LDB(B1, 0, 1); PG8_STAGE(PG8_SB(0, 0), b2, voffB);
;             PG8_BAR; PG8_WAIT_L(0); PG8_MMA(0, 1, At, B1); PG8_BAR;
;             PG8_LDA(At, 0, 1); PG8_STAGE(PG8_SA(0, 0), a2, voffA);
;             PG8_BAR; PG8_WAIT_L(0); PG8_MMA(1, 0, At, B0); PG8_BAR; PG8_SCHED;
;             PG8_STAGE(PG8_SB(0, 1), b2 + hstepB, voffB);
;             PG8_WAIT_V(6); PG8_BAR; PG8_MMA(1, 1, At, B1); PG8_BAR;
.LBB0_147:
	s_add_u32 s46, s26, 0xfff80080
	s_addc_u32 s47, s27, -1
	s_add_i32 s60, 0, 0x10000
	v_add_u32_e32 v144, s60, v147
	ds_read_b128 v[140:143], v144
	ds_read_b128 v[150:153], v144 offset:1024
	ds_read_b128 v[154:157], v144 offset:2048
	ds_read_b128 v[158:161], v144 offset:3072
	s_cmp_eq_u32 s51, 28
	s_cselect_b32 s49, s41, s47
	s_cselect_b32 s48, s29, s46
	s_cselect_b32 s47, s1, s50
	s_cselect_b32 s46, s20, s21
	v_lshl_add_u64 v[144:145], s[26:27], 0, v[136:137]
	s_add_i32 m0, s23, 0xc000
	ds_read_b128 v[162:165], v149
	ds_read_b128 v[166:169], v149 offset:1024
	ds_read_b128 v[170:173], v149 offset:2048
	ds_read_b128 v[174:177], v149 offset:3072
	ds_read_b128 v[178:181], v149 offset:4096
	ds_read_b128 v[182:185], v149 offset:5120
	ds_read_b128 v[186:189], v149 offset:6144
	ds_read_b128 v[190:193], v149 offset:7168
	global_load_lds_dwordx4 v[144:145], off
	v_lshl_add_u64 v[144:145], s[26:27], 0, v[138:139]
	s_add_i32 m0, s23, 0xe000
	s_nop 0
	global_load_lds_dwordx4 v[144:145], off
	s_waitcnt lgkmcnt(11)
	s_add_i32 s66, 0, 0x14000
	v_add_u32_e32 v144, s66, v147
	s_add_i32 s60, s60, s64
	ds_read_b128 v[194:197], v144
	ds_read_b128 v[198:201], v144 offset:1024
	ds_read_b128 v[202:205], v144 offset:2048
	ds_read_b128 v[220:223], v144 offset:3072
	s_waitcnt vmcnt(8) lgkmcnt(0)
	s_barrier
	v_mfma_f32_16x16x32_f16 v[126:129], v[140:143], v[162:165], v[126:129]
	v_mfma_f32_16x16x32_f16 v[122:125], v[154:157], v[162:165], v[122:125]
	v_mfma_f32_16x16x32_f16 v[110:113], v[140:143], v[170:173], v[110:113]
	v_mfma_f32_16x16x32_f16 v[106:109], v[154:157], v[170:173], v[106:109]
	v_mfma_f32_16x16x32_f16 v[94:97], v[140:143], v[178:181], v[94:97]
	v_mfma_f32_16x16x32_f16 v[90:93], v[154:157], v[178:181], v[90:93]
	v_mfma_f32_16x16x32_f16 v[78:81], v[140:143], v[186:189], v[78:81]
	v_mfma_f32_16x16x32_f16 v[74:77], v[154:157], v[186:189], v[74:77]
	v_mfma_f32_16x16x32_f16 v[126:129], v[150:153], v[166:169], v[126:129]
	v_mfma_f32_16x16x32_f16 v[122:125], v[158:161], v[166:169], v[122:125]
	v_mfma_f32_16x16x32_f16 v[110:113], v[150:153], v[174:177], v[110:113]
	v_mfma_f32_16x16x32_f16 v[106:109], v[158:161], v[174:177], v[106:109]
	v_mfma_f32_16x16x32_f16 v[94:97], v[150:153], v[182:185], v[94:97]
	v_mfma_f32_16x16x32_f16 v[90:93], v[158:161], v[182:185], v[90:93]
	v_mfma_f32_16x16x32_f16 v[78:81], v[150:153], v[190:193], v[78:81]
	v_mfma_f32_16x16x32_f16 v[74:77], v[158:161], v[190:193], v[74:77]
	v_mfma_f32_16x16x32_f16 v[118:121], v[194:197], v[162:165], v[118:121]
	v_mfma_f32_16x16x32_f16 v[114:117], v[202:205], v[162:165], v[114:117]
	v_mfma_f32_16x16x32_f16 v[102:105], v[194:197], v[170:173], v[102:105]
	v_mfma_f32_16x16x32_f16 v[98:101], v[202:205], v[170:173], v[98:101]
	v_mfma_f32_16x16x32_f16 v[86:89], v[194:197], v[178:181], v[86:89]
	v_mfma_f32_16x16x32_f16 v[82:85], v[202:205], v[178:181], v[82:85]
	v_mfma_f32_16x16x32_f16 v[70:73], v[194:197], v[186:189], v[70:73]
	v_mfma_f32_16x16x32_f16 v[66:69], v[202:205], v[186:189], v[66:69]
	v_mfma_f32_16x16x32_f16 v[118:121], v[198:201], v[166:169], v[118:121]
	v_mfma_f32_16x16x32_f16 v[114:117], v[220:223], v[166:169], v[114:117]
	v_mfma_f32_16x16x32_f16 v[102:105], v[198:201], v[174:177], v[102:105]
	v_mfma_f32_16x16x32_f16 v[98:101], v[220:223], v[174:177], v[98:101]
	v_mfma_f32_16x16x32_f16 v[86:89], v[198:201], v[182:185], v[86:89]
	v_mfma_f32_16x16x32_f16 v[82:85], v[220:223], v[182:185], v[82:85]
	v_mfma_f32_16x16x32_f16 v[70:73], v[198:201], v[190:193], v[70:73]
	v_mfma_f32_16x16x32_f16 v[66:69], v[220:223], v[190:193], v[66:69]
	s_barrier
	v_lshl_add_u64 v[144:145], s[46:47], 0, v[0:1]
	s_mov_b32 m0, s60
	v_lshl_add_u64 v[206:207], s[46:47], 0, v[134:135]
	global_load_lds_dwordx4 v[144:145], off
	s_add_i32 m0, s60, 0x2000
	s_nop 0
	global_load_lds_dwordx4 v[206:207], off
	s_mov_b32 m0, s23
	v_lshl_add_u64 v[212:213], s[48:49], 0, v[130:131]
	ds_read_b128 v[162:165], v149 offset:16384
	ds_read_b128 v[166:169], v149 offset:17408
	ds_read_b128 v[170:173], v149 offset:18432
	ds_read_b128 v[174:177], v149 offset:19456
	ds_read_b128 v[178:181], v149 offset:20480
	ds_read_b128 v[182:185], v149 offset:21504
	ds_read_b128 v[186:189], v149 offset:22528
	ds_read_b128 v[190:193], v149 offset:23552
	global_load_lds_dwordx4 v[212:213], off
	v_lshl_add_u64 v[214:215], s[48:49], 0, v[132:133]
	s_mov_b32 m0, s71
	s_nop 0
	global_load_lds_dwordx4 v[214:215], off
	s_waitcnt vmcnt(6) lgkmcnt(0)
	s_barrier
	v_mfma_f32_16x16x32_f16 v[62:65], v[140:143], v[162:165], v[62:65]
	v_mfma_f32_16x16x32_f16 v[58:61], v[154:157], v[162:165], v[58:61]
	v_mfma_f32_16x16x32_f16 v[46:49], v[140:143], v[170:173], v[46:49]
	v_mfma_f32_16x16x32_f16 v[42:45], v[154:157], v[170:173], v[42:45]
	v_mfma_f32_16x16x32_f16 v[30:33], v[140:143], v[178:181], v[30:33]
	v_mfma_f32_16x16x32_f16 v[26:29], v[154:157], v[178:181], v[26:29]
	v_mfma_f32_16x16x32_f16 v[14:17], v[140:143], v[186:189], v[14:17]
	v_mfma_f32_16x16x32_f16 v[10:13], v[154:157], v[186:189], v[10:13]
	v_mfma_f32_16x16x32_f16 v[62:65], v[150:153], v[166:169], v[62:65]
	v_mfma_f32_16x16x32_f16 v[58:61], v[158:161], v[166:169], v[58:61]
	v_mfma_f32_16x16x32_f16 v[46:49], v[150:153], v[174:177], v[46:49]
	v_mfma_f32_16x16x32_f16 v[42:45], v[158:161], v[174:177], v[42:45]
	v_mfma_f32_16x16x32_f16 v[30:33], v[150:153], v[182:185], v[30:33]
	v_mfma_f32_16x16x32_f16 v[26:29], v[158:161], v[182:185], v[26:29]
	v_mfma_f32_16x16x32_f16 v[14:17], v[150:153], v[190:193], v[14:17]
	v_mfma_f32_16x16x32_f16 v[10:13], v[158:161], v[190:193], v[10:13]
	v_mfma_f32_16x16x32_f16 v[54:57], v[194:197], v[162:165], v[54:57]
	v_mfma_f32_16x16x32_f16 v[50:53], v[202:205], v[162:165], v[50:53]
	v_mfma_f32_16x16x32_f16 v[38:41], v[194:197], v[170:173], v[38:41]
	v_mfma_f32_16x16x32_f16 v[34:37], v[202:205], v[170:173], v[34:37]
	v_mfma_f32_16x16x32_f16 v[22:25], v[194:197], v[178:181], v[22:25]
	v_mfma_f32_16x16x32_f16 v[18:21], v[202:205], v[178:181], v[18:21]
	v_mfma_f32_16x16x32_f16 v[6:9], v[194:197], v[186:189], v[6:9]
	v_mfma_f32_16x16x32_f16 v[2:5], v[202:205], v[186:189], v[2:5]
	v_mfma_f32_16x16x32_f16 v[54:57], v[198:201], v[166:169], v[54:57]
	v_mfma_f32_16x16x32_f16 v[50:53], v[220:223], v[166:169], v[50:53]
	v_mfma_f32_16x16x32_f16 v[38:41], v[198:201], v[174:177], v[38:41]
	v_mfma_f32_16x16x32_f16 v[34:37], v[220:223], v[174:177], v[34:37]
	v_mfma_f32_16x16x32_f16 v[22:25], v[198:201], v[182:185], v[22:25]
	v_mfma_f32_16x16x32_f16 v[18:21], v[220:223], v[182:185], v[18:21]
	v_mfma_f32_16x16x32_f16 v[6:9], v[198:201], v[190:193], v[6:9]
	v_mfma_f32_16x16x32_f16 v[2:5], v[220:223], v[190:193], v[2:5]
	s_barrier
; #define PG8_STAGE(bufoff, gbase, voff) do { _Pragma("unroll") for (int _i = 0; _i < 2; ++_i) \
;         __builtin_amdgcn_global_load_lds((const unsigned*)((const char*)(gbase) + (voff)[_i]), (LAS unsigned*)(lds + (bufoff) + ldsw + _i * 8192), 16, 0, 0); } while (0)
; #define PG8_LDA(dst, b, h) do { _Pragma("unroll") for (int m = 0; m < 4; ++m) _Pragma("unroll") for (int k = 0; k < 2; ++k) dst[m][k] = *(const LAS h16x8*)(lds + PG8_SA(b, h) + aoff + m * 2048 + k * 1024); } while (0)
; #define PG8_LDB(dst, b, h) do { _Pragma("unroll") for (int n = 0; n < 2; ++n) _Pragma("unroll") for (int k = 0; k < 2; ++k) dst[n][k] = *(const LAS h16x8*)(lds + PG8_SB(b, h) + boff + n * 2048 + k * 1024); } while (0)
; #define PG8_MMA(ai, bj, At, Bt_) do { __builtin_amdgcn_s_setprio(1); _Pragma("unroll") for (int m = 0; m < 4; ++m) _Pragma("unroll") for (int n = 0; n < 2; ++n) _Pragma("unroll") for (int k = 0; k < 2; ++k) \
;         acc[ai][bj][m][n] = __builtin_amdgcn_mfma_f32_16x16x32_f16(Bt_[n][k], At[m][k], acc[ai][bj][m][n], 0, 0, 0); __builtin_amdgcn_s_setprio(0); } while (0)
; #define PG8_WAIT_V(n) asm volatile("s_waitcnt vmcnt(" #n ")" ::: "memory")
; #define PG8_WAIT_L(n) asm volatile("s_waitcnt lgkmcnt(" #n ")" ::: "memory")
; #define PG8_BAR __builtin_amdgcn_s_barrier()
; #define PG8_SCHED __builtin_amdgcn_sched_barrier(0)
; template <class Epi, class AMap>
; __device__ __forceinline__ void gemm_phase(LAS unsigned char* lds, const AMap am, const int lda, const h16* Bt, const int ldb, const int M, const int N, const int K, const Epi& E) {
;     ...
;             PG8_STAGE(PG8_SB(0, 1), b2 + hstepB, voffB);
;             PG8_WAIT_V(6); PG8_BAR; PG8_MMA(1, 1, At, B1); PG8_BAR;
;             PG8_LDB(B0, 1, 0); PG8_SCHED; PG8_LDA(At, 1, 0); PG8_STAGE(PG8_SA(0, 1), a2 + hstepA, voffA);
;             PG8_WAIT_L(8); PG8_BAR; PG8_WAIT_L(0); PG8_MMA(0, 0, At, B0); PG8_BAR; PG8_SCHED;
;             PG8_LDB(B1, 1, 1); PG8_STAGE(PG8_SB(1, 0), b3, voffB);
;             PG8_BAR; PG8_WAIT_L(0); PG8_MMA(0, 1, At, B1); PG8_BAR;
;             PG8_LDA(At, 1, 1); PG8_STAGE(PG8_SA(1, 0), a3, voffA);
;             PG8_BAR; PG8_WAIT_L(0); PG8_MMA(1, 0, At, B0); PG8_BAR; PG8_SCHED;
;             PG8_STAGE(PG8_SB(1, 1), b3 + hstepB, voffB);
;             PG8_WAIT_V(6); PG8_BAR; PG8_MMA(1, 1, At, B1); PG8_BAR;
;         }
	s_add_u32 s78, s46, 0x80000
	s_addc_u32 s79, s47, 0
	s_add_i32 s60, s66, s64
	v_lshl_add_u64 v[232:233], s[78:79], 0, v[0:1]
	s_mov_b32 m0, s60
	s_nop 0
	global_load_lds_dwordx4 v[232:233], off
	v_lshl_add_u64 v[232:233], s[78:79], 0, v[134:135]
	s_add_i32 m0, s60, 0x2000
	s_nop 0
	global_load_lds_dwordx4 v[232:233], off
	s_add_i32 s60, 0, 0x18000
	v_add_u32_e32 v234, s60, v147
	ds_read_b128 v[140:143], v234
	ds_read_b128 v[150:153], v234 offset:1024
	ds_read_b128 v[154:157], v234 offset:2048
	ds_read_b128 v[158:161], v234 offset:3072
	s_add_u32 s48, s48, 0x80000
	s_addc_u32 s49, s49, 0
	s_mov_b32 m0, s72
	v_lshl_add_u64 v[232:233], s[48:49], 0, v[130:131]
	ds_read_b128 v[162:165], v149 offset:32768
	ds_read_b128 v[166:169], v149 offset:33792
	ds_read_b128 v[170:173], v149 offset:34816
	ds_read_b128 v[174:177], v149 offset:35840
	ds_read_b128 v[178:181], v149 offset:36864
	ds_read_b128 v[182:185], v149 offset:37888
	ds_read_b128 v[186:189], v149 offset:38912
	ds_read_b128 v[190:193], v149 offset:39936
	global_load_lds_dwordx4 v[232:233], off
	v_lshl_add_u64 v[232:233], s[48:49], 0, v[132:133]
	s_mov_b32 m0, s73
	s_nop 0
	global_load_lds_dwordx4 v[232:233], off
	s_waitcnt lgkmcnt(11)
	s_add_i32 s48, 0, 0x1c000
	s_add_i32 s49, s60, s64
	v_add_u32_e32 v216, s48, v147
	v_lshl_add_u64 v[144:145], v[144:145], 0, s[92:93]
	s_mov_b32 m0, s49
	ds_read_b128 v[194:197], v216
	ds_read_b128 v[198:201], v216 offset:1024
	ds_read_b128 v[202:205], v216 offset:2048
	ds_read_b128 v[220:223], v216 offset:3072
	s_waitcnt vmcnt(8) lgkmcnt(0)
	s_barrier
	v_mfma_f32_16x16x32_f16 v[126:129], v[140:143], v[162:165], v[126:129]
	v_mfma_f32_16x16x32_f16 v[122:125], v[154:157], v[162:165], v[122:125]
	v_mfma_f32_16x16x32_f16 v[110:113], v[140:143], v[170:173], v[110:113]
	v_mfma_f32_16x16x32_f16 v[106:109], v[154:157], v[170:173], v[106:109]
	v_mfma_f32_16x16x32_f16 v[94:97], v[140:143], v[178:181], v[94:97]
	v_mfma_f32_16x16x32_f16 v[90:93], v[154:157], v[178:181], v[90:93]
	v_mfma_f32_16x16x32_f16 v[78:81], v[140:143], v[186:189], v[78:81]
	v_mfma_f32_16x16x32_f16 v[74:77], v[154:157], v[186:189], v[74:77]
	v_mfma_f32_16x16x32_f16 v[126:129], v[150:153], v[166:169], v[126:129]
	v_mfma_f32_16x16x32_f16 v[122:125], v[158:161], v[166:169], v[122:125]
	v_mfma_f32_16x16x32_f16 v[110:113], v[150:153], v[174:177], v[110:113]
	v_mfma_f32_16x16x32_f16 v[106:109], v[158:161], v[174:177], v[106:109]
	v_mfma_f32_16x16x32_f16 v[94:97], v[150:153], v[182:185], v[94:97]
	v_mfma_f32_16x16x32_f16 v[90:93], v[158:161], v[182:185], v[90:93]
	v_mfma_f32_16x16x32_f16 v[78:81], v[150:153], v[190:193], v[78:81]
	v_mfma_f32_16x16x32_f16 v[74:77], v[158:161], v[190:193], v[74:77]
	v_mfma_f32_16x16x32_f16 v[118:121], v[194:197], v[162:165], v[118:121]
	v_mfma_f32_16x16x32_f16 v[114:117], v[202:205], v[162:165], v[114:117]
	v_mfma_f32_16x16x32_f16 v[102:105], v[194:197], v[170:173], v[102:105]
	v_mfma_f32_16x16x32_f16 v[98:101], v[202:205], v[170:173], v[98:101]
	v_mfma_f32_16x16x32_f16 v[86:89], v[194:197], v[178:181], v[86:89]
	v_mfma_f32_16x16x32_f16 v[82:85], v[202:205], v[178:181], v[82:85]
	v_mfma_f32_16x16x32_f16 v[70:73], v[194:197], v[186:189], v[70:73]
	v_mfma_f32_16x16x32_f16 v[66:69], v[202:205], v[186:189], v[66:69]
	v_mfma_f32_16x16x32_f16 v[118:121], v[198:201], v[166:169], v[118:121]
	v_mfma_f32_16x16x32_f16 v[114:117], v[220:223], v[166:169], v[114:117]
	v_mfma_f32_16x16x32_f16 v[102:105], v[198:201], v[174:177], v[102:105]
	v_mfma_f32_16x16x32_f16 v[98:101], v[220:223], v[174:177], v[98:101]
	v_mfma_f32_16x16x32_f16 v[86:89], v[198:201], v[182:185], v[86:89]
	v_mfma_f32_16x16x32_f16 v[82:85], v[220:223], v[182:185], v[82:85]
	v_mfma_f32_16x16x32_f16 v[70:73], v[198:201], v[190:193], v[70:73]
	v_mfma_f32_16x16x32_f16 v[66:69], v[220:223], v[190:193], v[66:69]
	s_barrier
	global_load_lds_dwordx4 v[144:145], off
	v_lshl_add_u64 v[144:145], v[206:207], 0, s[92:93]
	s_add_i32 m0, s49, 0x2000
	s_nop 0
	global_load_lds_dwordx4 v[144:145], off
	s_mov_b32 m0, s74
	v_lshl_add_u64 v[144:145], v[212:213], 0, s[92:93]
	ds_read_b128 v[162:165], v149 offset:49152
	ds_read_b128 v[166:169], v149 offset:50176
	ds_read_b128 v[170:173], v149 offset:51200
	ds_read_b128 v[174:177], v149 offset:52224
	ds_read_b128 v[178:181], v149 offset:53248
	ds_read_b128 v[182:185], v149 offset:54272
	ds_read_b128 v[186:189], v149 offset:55296
	ds_read_b128 v[190:193], v149 offset:56320
	global_load_lds_dwordx4 v[144:145], off
	v_lshl_add_u64 v[144:145], v[214:215], 0, s[92:93]
	s_mov_b32 m0, s75
	s_nop 0
	global_load_lds_dwordx4 v[144:145], off
	s_add_u32 s46, s46, 0x80080
	s_addc_u32 s47, s47, 0
	s_add_i32 s48, s48, s64
	v_lshl_add_u64 v[232:233], s[46:47], 0, v[0:1]
	s_mov_b32 m0, s48
	s_nop 0
	global_load_lds_dwordx4 v[232:233], off
	v_lshl_add_u64 v[232:233], s[46:47], 0, v[134:135]
	s_add_i32 m0, s48, 0x2000
	s_nop 0
	global_load_lds_dwordx4 v[232:233], off
	s_add_i32 s51, s51, 2
	s_add_u32 s26, s26, 0x100
	s_addc_u32 s27, s27, 0
	s_add_u32 s21, s21, 0x100
	s_addc_u32 s50, s50, 0
	s_cmp_gt_u32 s51, 29
	s_waitcnt vmcnt(8) lgkmcnt(0)
	s_barrier
; #define PG8_MMA(ai, bj, At, Bt_) do { __builtin_amdgcn_s_setprio(1); _Pragma("unroll") for (int m = 0; m < 4; ++m) _Pragma("unroll") for (int n = 0; n < 2; ++n) _Pragma("unroll") for (int k = 0; k < 2; ++k) \
;         acc[ai][bj][m][n] = __builtin_amdgcn_mfma_f32_16x16x32_f16(Bt_[n][k], At[m][k], acc[ai][bj][m][n], 0, 0, 0); __builtin_amdgcn_s_setprio(0); } while (0)
; #define PG8_WAIT_V(n) asm volatile("s_waitcnt vmcnt(" #n ")" ::: "memory")
; #define PG8_BAR __builtin_amdgcn_s_barrier()
; template <class Epi, class AMap>
; __device__ __forceinline__ void gemm_phase(LAS unsigned char* lds, const AMap am, const int lda, const h16* Bt, const int ldb, const int M, const int N, const int K, const Epi& E) {
;     ...
;             PG8_WAIT_V(6); PG8_BAR; PG8_MMA(1, 1, At, B1); PG8_BAR;
;         }
;         E(acc, cur, wr, wc, fr, fq);
;     __device__ __forceinline__ void operator()(const f32x4 (&acc)[2][2][4][2], const Unit& u, int wr, int wc, int fr, int fq) const {
;         EPI_ROWS_PERM
; #pragma unroll
;         for (int ai = 0; ai < 2; ++ai)
; #pragma unroll
;             for (int m = 0; m < 4; ++m) { const size_t off = (size_t)(row0 + ai * 128 + m * 16) * DM + colt;
; #pragma unroll
;                 for (int bj = 0; bj < 2; ++bj) {
;                     const h16x8 x = *(const h16x8*)(X + off + bj * 128);
	v_mfma_f32_16x16x32_f16 v[62:65], v[140:143], v[162:165], v[62:65]
	v_mfma_f32_16x16x32_f16 v[58:61], v[154:157], v[162:165], v[58:61]
	v_mfma_f32_16x16x32_f16 v[46:49], v[140:143], v[170:173], v[46:49]
	v_mfma_f32_16x16x32_f16 v[42:45], v[154:157], v[170:173], v[42:45]
	v_mfma_f32_16x16x32_f16 v[30:33], v[140:143], v[178:181], v[30:33]
	v_mfma_f32_16x16x32_f16 v[26:29], v[154:157], v[178:181], v[26:29]
	v_mfma_f32_16x16x32_f16 v[14:17], v[140:143], v[186:189], v[14:17]
	v_mfma_f32_16x16x32_f16 v[10:13], v[154:157], v[186:189], v[10:13]
	v_mfma_f32_16x16x32_f16 v[62:65], v[150:153], v[166:169], v[62:65]
	v_mfma_f32_16x16x32_f16 v[58:61], v[158:161], v[166:169], v[58:61]
	v_mfma_f32_16x16x32_f16 v[46:49], v[150:153], v[174:177], v[46:49]
	v_mfma_f32_16x16x32_f16 v[42:45], v[158:161], v[174:177], v[42:45]
	v_mfma_f32_16x16x32_f16 v[30:33], v[150:153], v[182:185], v[30:33]
	v_mfma_f32_16x16x32_f16 v[26:29], v[158:161], v[182:185], v[26:29]
	v_mfma_f32_16x16x32_f16 v[14:17], v[150:153], v[190:193], v[14:17]
	v_mfma_f32_16x16x32_f16 v[10:13], v[158:161], v[190:193], v[10:13]
	v_mfma_f32_16x16x32_f16 v[54:57], v[194:197], v[162:165], v[54:57]
	v_mfma_f32_16x16x32_f16 v[50:53], v[202:205], v[162:165], v[50:53]
	v_mfma_f32_16x16x32_f16 v[38:41], v[194:197], v[170:173], v[38:41]
	v_mfma_f32_16x16x32_f16 v[34:37], v[202:205], v[170:173], v[34:37]
	v_mfma_f32_16x16x32_f16 v[22:25], v[194:197], v[178:181], v[22:25]
	v_mfma_f32_16x16x32_f16 v[18:21], v[202:205], v[178:181], v[18:21]
	v_mfma_f32_16x16x32_f16 v[6:9], v[194:197], v[186:189], v[6:9]
	v_mfma_f32_16x16x32_f16 v[2:5], v[202:205], v[186:189], v[2:5]
	v_mfma_f32_16x16x32_f16 v[54:57], v[198:201], v[166:169], v[54:57]
	v_mfma_f32_16x16x32_f16 v[50:53], v[220:223], v[166:169], v[50:53]
	v_mfma_f32_16x16x32_f16 v[38:41], v[198:201], v[174:177], v[38:41]
	v_mfma_f32_16x16x32_f16 v[34:37], v[220:223], v[174:177], v[34:37]
	v_mfma_f32_16x16x32_f16 v[22:25], v[198:201], v[182:185], v[22:25]
	v_mfma_f32_16x16x32_f16 v[18:21], v[220:223], v[182:185], v[18:21]
	v_mfma_f32_16x16x32_f16 v[6:9], v[198:201], v[190:193], v[6:9]
	v_mfma_f32_16x16x32_f16 v[2:5], v[220:223], v[190:193], v[2:5]
	s_barrier
	s_cbranch_scc0 .LBB0_147
	v_lshl_add_u32 v144, s22, 8, v146
	v_lshl_or_b32 v142, s35, 8, v148
	v_ashrrev_i32_e32 v145, 31, v144
	v_ashrrev_i32_e32 v143, 31, v142
	v_lshlrev_b64 v[140:141], 11, v[144:145]
	v_lshl_add_u64 v[140:141], v[140:141], 0, v[142:143]
	v_lshlrev_b64 v[140:141], 1, v[140:141]
	v_lshl_add_u64 v[154:155], s[94:95], 0, v[140:141]
	s_mov_b32 s101, 0
	global_load_dwordx4 v[158:161], v[154:155], off
	global_load_dwordx4 v[162:165], v[154:155], off offset:256
	s_mov_b32 s100, 0x10000
	v_lshl_add_u64 v[232:233], v[154:155], 0, s[100:101]
	global_load_dwordx4 v[166:169], v[232:233], off
	global_load_dwordx4 v[170:173], v[232:233], off offset:256
	s_mov_b32 s100, 0x20000
	v_lshl_add_u64 v[232:233], v[154:155], 0, s[100:101]
	global_load_dwordx4 v[174:177], v[232:233], off
	global_load_dwordx4 v[178:181], v[232:233], off offset:256
	s_mov_b32 s100, 0x30000
	v_lshl_add_u64 v[232:233], v[154:155], 0, s[100:101]
	global_load_dwordx4 v[182:185], v[232:233], off
	global_load_dwordx4 v[186:189], v[232:233], off offset:256
	s_mov_b32 s100, 0x80000
	v_lshl_add_u64 v[232:233], v[154:155], 0, s[100:101]
	global_load_dwordx4 v[190:193], v[232:233], off
	global_load_dwordx4 v[194:197], v[232:233], off offset:256
	s_mov_b32 s100, 0x90000
	v_lshl_add_u64 v[232:233], v[154:155], 0, s[100:101]
	global_load_dwordx4 v[198:201], v[232:233], off
	global_load_dwordx4 v[202:205], v[232:233], off offset:256
	s_mov_b32 s100, 0xa0000
	v_lshl_add_u64 v[232:233], v[154:155], 0, s[100:101]
	global_load_dwordx4 v[212:215], v[232:233], off
	global_load_dwordx4 v[220:223], v[232:233], off offset:256
	s_mov_b32 s100, 0xb0000
	v_lshl_add_u64 v[232:233], v[154:155], 0, s[100:101]
	global_load_dwordx4 v[224:227], v[232:233], off
	global_load_dwordx4 v[228:231], v[232:233], off offset:256
	s_mov_b64 s[2:3], 0xb0000
	s_and_b64 vcc, exec, s[38:39]
	s_mov_b32 s22, s40
	s_mov_b64 s[46:47], s[44:45]
	s_mov_b64 s[26:27], s[42:43]
	s_movk_i32 s66, 0x80
	s_cmpk_gt_u32 s62, 0xff
	s_cbranch_scc1 .Lgx2
	s_barrier

; #define PG8_STAGE(bufoff, gbase, voff) do { _Pragma("unroll") for (int _i = 0; _i < 2; ++_i) \
;         __builtin_amdgcn_global_load_lds((const unsigned*)((const char*)(gbase) + (voff)[_i]), (LAS unsigned*)(lds + (bufoff) + ldsw + _i * 8192), 16, 0, 0); } while (0)
; #define PG8_LDA(dst, b, h) do { _Pragma("unroll") for (int m = 0; m < 4; ++m) _Pragma("unroll") for (int k = 0; k < 2; ++k) dst[m][k] = *(const LAS h16x8*)(lds + PG8_SA(b, h) + aoff + m * 2048 + k * 1024); } while (0)
; #define PG8_LDB(dst, b, h) do { _Pragma("unroll") for (int n = 0; n < 2; ++n) _Pragma("unroll") for (int k = 0; k < 2; ++k) dst[n][k] = *(const LAS h16x8*)(lds + PG8_SB(b, h) + boff + n * 2048 + k * 1024); } while (0)
; #define PG8_MMA(ai, bj, At, Bt_) do { __builtin_amdgcn_s_setprio(1); _Pragma("unroll") for (int m = 0; m < 4; ++m) _Pragma("unroll") for (int n = 0; n < 2; ++n) _Pragma("unroll") for (int k = 0; k < 2; ++k) \
;         acc[ai][bj][m][n] = __builtin_amdgcn_mfma_f32_16x16x32_f16(Bt_[n][k], At[m][k], acc[ai][bj][m][n], 0, 0, 0); __builtin_amdgcn_s_setprio(0); } while (0)
; #define PG8_WAIT_V(n) asm volatile("s_waitcnt vmcnt(" #n ")" ::: "memory")
; #define PG8_WAIT_L(n) asm volatile("s_waitcnt lgkmcnt(" #n ")" ::: "memory")
; template <class Epi, class AMap>
; __device__ __forceinline__ void gemm_phase(LAS unsigned char* lds, const AMap am, const int lda, const h16* Bt, const int ldb, const int M, const int N, const int K, const Epi& E) {
;     ...
;             const bool last = (t == nt - 2);
;             const char* a1 = cA + (size_t)(t + 1) * kstep;
;             const char* a2 = last ? nA : cA + (size_t)(t + 2) * kstep; const char* b2 = last ? nB : cB + (size_t)(t + 2) * kstep;
;             const char* a3 = a2 + kstep; const char* b3 = b2 + kstep;
;             PG8_LDB(B0, 0, 0); PG8_SCHED; PG8_LDA(At, 0, 0); PG8_STAGE(PG8_SA(1, 1), a1 + hstepA, voffA);
;             PG8_WAIT_L(8); PG8_BAR; PG8_WAIT_L(0); PG8_MMA(0, 0, At, B0); PG8_BAR; PG8_SCHED;
;             PG8_LDB(B1, 0, 1); PG8_STAGE(PG8_SB(0, 0), b2, voffB);
;             PG8_BAR; PG8_WAIT_L(0); PG8_MMA(0, 1, At, B1); PG8_BAR;
;             PG8_LDA(At, 0, 1); PG8_STAGE(PG8_SA(0, 0), a2, voffA);
;             PG8_BAR; PG8_WAIT_L(0); PG8_MMA(1, 0, At, B0); PG8_BAR; PG8_SCHED;
;             PG8_STAGE(PG8_SB(0, 1), b2 + hstepB, voffB);
;             PG8_WAIT_V(6); PG8_BAR; PG8_MMA(1, 1, At, B1); PG8_BAR;
.LBB0_621:
	s_add_i32 s51, s26, 2
	s_add_u32 s0, s22, 0x100
	s_addc_u32 s1, s23, 0
	s_add_i32 s60, 0, 0x10000
	v_add_u32_e32 v152, s60, v155
	ds_read_b128 v[90:93], v152
	ds_read_b128 v[94:97], v152 offset:1024
	ds_read_b128 v[148:151], v152 offset:2048
	ds_read_b128 v[158:161], v152 offset:3072
	s_cmp_eq_u32 s82, s26
	s_cselect_b32 s26, s21, s29
	s_cselect_b32 s49, s65, s1
	s_cselect_b32 s48, s64, s0
	s_cselect_b32 s27, s20, s45
	v_lshl_add_u64 v[152:153], s[22:23], 0, v[144:145]
	s_add_i32 m0, s76, 0xc000
	ds_read_b128 v[162:165], v157
	ds_read_b128 v[166:169], v157 offset:1024
	ds_read_b128 v[170:173], v157 offset:2048
	ds_read_b128 v[174:177], v157 offset:3072
	ds_read_b128 v[178:181], v157 offset:4096
	ds_read_b128 v[182:185], v157 offset:5120
	ds_read_b128 v[186:189], v157 offset:6144
	ds_read_b128 v[190:193], v157 offset:7168
	global_load_lds_dwordx4 v[152:153], off
	v_lshl_add_u64 v[152:153], s[22:23], 0, v[146:147]
	s_add_i32 m0, s76, 0xe000
	s_nop 0
	global_load_lds_dwordx4 v[152:153], off
	s_waitcnt lgkmcnt(11)
	s_add_i32 s62, 0, 0x14000
	v_add_u32_e32 v152, s62, v155
	s_add_i32 s22, s60, s73
	ds_read_b128 v[194:197], v152
	ds_read_b128 v[198:201], v152 offset:1024
	ds_read_b128 v[202:205], v152 offset:2048
	ds_read_b128 v[220:223], v152 offset:3072
	s_waitcnt vmcnt(8) lgkmcnt(0)
	s_barrier
	v_mfma_f32_16x16x32_f16 v[130:133], v[90:93], v[162:165], v[130:133]
	v_mfma_f32_16x16x32_f16 v[134:137], v[148:151], v[162:165], v[134:137]
	v_mfma_f32_16x16x32_f16 v[126:129], v[90:93], v[170:173], v[126:129]
	v_mfma_f32_16x16x32_f16 v[122:125], v[148:151], v[170:173], v[122:125]
	v_mfma_f32_16x16x32_f16 v[118:121], v[90:93], v[178:181], v[118:121]
	v_mfma_f32_16x16x32_f16 v[114:117], v[148:151], v[178:181], v[114:117]
	v_mfma_f32_16x16x32_f16 v[110:113], v[90:93], v[186:189], v[110:113]
	v_mfma_f32_16x16x32_f16 v[106:109], v[148:151], v[186:189], v[106:109]
	v_mfma_f32_16x16x32_f16 v[130:133], v[94:97], v[166:169], v[130:133]
	v_mfma_f32_16x16x32_f16 v[134:137], v[158:161], v[166:169], v[134:137]
	v_mfma_f32_16x16x32_f16 v[126:129], v[94:97], v[174:177], v[126:129]
	v_mfma_f32_16x16x32_f16 v[122:125], v[158:161], v[174:177], v[122:125]
	v_mfma_f32_16x16x32_f16 v[118:121], v[94:97], v[182:185], v[118:121]
	v_mfma_f32_16x16x32_f16 v[114:117], v[158:161], v[182:185], v[114:117]
	v_mfma_f32_16x16x32_f16 v[110:113], v[94:97], v[190:193], v[110:113]
	v_mfma_f32_16x16x32_f16 v[106:109], v[158:161], v[190:193], v[106:109]
	v_mfma_f32_16x16x32_f16 v[62:65], v[194:197], v[162:165], v[62:65]
	v_mfma_f32_16x16x32_f16 v[58:61], v[202:205], v[162:165], v[58:61]
	v_mfma_f32_16x16x32_f16 v[54:57], v[194:197], v[170:173], v[54:57]
	v_mfma_f32_16x16x32_f16 v[50:53], v[202:205], v[170:173], v[50:53]
	v_mfma_f32_16x16x32_f16 v[46:49], v[194:197], v[178:181], v[46:49]
	v_mfma_f32_16x16x32_f16 v[42:45], v[202:205], v[178:181], v[42:45]
	v_mfma_f32_16x16x32_f16 v[38:41], v[194:197], v[186:189], v[38:41]
	v_mfma_f32_16x16x32_f16 v[34:37], v[202:205], v[186:189], v[34:37]
	v_mfma_f32_16x16x32_f16 v[62:65], v[198:201], v[166:169], v[62:65]
	v_mfma_f32_16x16x32_f16 v[58:61], v[220:223], v[166:169], v[58:61]
	v_mfma_f32_16x16x32_f16 v[54:57], v[198:201], v[174:177], v[54:57]
	v_mfma_f32_16x16x32_f16 v[50:53], v[220:223], v[174:177], v[50:53]
	v_mfma_f32_16x16x32_f16 v[46:49], v[198:201], v[182:185], v[46:49]
	v_mfma_f32_16x16x32_f16 v[42:45], v[220:223], v[182:185], v[42:45]
	v_mfma_f32_16x16x32_f16 v[38:41], v[198:201], v[190:193], v[38:41]
	v_mfma_f32_16x16x32_f16 v[34:37], v[220:223], v[190:193], v[34:37]
	s_barrier
	v_lshl_add_u64 v[152:153], s[26:27], 0, v[0:1]
	s_mov_b32 m0, s22
	v_lshl_add_u64 v[206:207], s[26:27], 0, v[142:143]
	global_load_lds_dwordx4 v[152:153], off
	s_add_i32 m0, s22, 0x2000
	s_nop 0
	global_load_lds_dwordx4 v[206:207], off
	s_mov_b32 m0, s76
	v_lshl_add_u64 v[212:213], s[48:49], 0, v[138:139]
	ds_read_b128 v[162:165], v157 offset:16384
	ds_read_b128 v[166:169], v157 offset:17408
	ds_read_b128 v[170:173], v157 offset:18432
	ds_read_b128 v[174:177], v157 offset:19456
	ds_read_b128 v[178:181], v157 offset:20480
	ds_read_b128 v[182:185], v157 offset:21504
	ds_read_b128 v[186:189], v157 offset:22528
	ds_read_b128 v[190:193], v157 offset:23552
	global_load_lds_dwordx4 v[212:213], off
	v_lshl_add_u64 v[224:225], s[48:49], 0, v[140:141]
	s_mov_b32 m0, s77
	s_nop 0
	global_load_lds_dwordx4 v[224:225], off
	s_waitcnt vmcnt(6) lgkmcnt(0)
	s_barrier
	v_mfma_f32_16x16x32_f16 v[102:105], v[90:93], v[162:165], v[102:105]
	v_mfma_f32_16x16x32_f16 v[98:101], v[148:151], v[162:165], v[98:101]
	v_mfma_f32_16x16x32_f16 v[86:89], v[90:93], v[170:173], v[86:89]
	v_mfma_f32_16x16x32_f16 v[82:85], v[148:151], v[170:173], v[82:85]
	v_mfma_f32_16x16x32_f16 v[78:81], v[90:93], v[178:181], v[78:81]
	v_mfma_f32_16x16x32_f16 v[74:77], v[148:151], v[178:181], v[74:77]
	v_mfma_f32_16x16x32_f16 v[70:73], v[90:93], v[186:189], v[70:73]
	v_mfma_f32_16x16x32_f16 v[66:69], v[148:151], v[186:189], v[66:69]
	v_mfma_f32_16x16x32_f16 v[102:105], v[94:97], v[166:169], v[102:105]
	v_mfma_f32_16x16x32_f16 v[98:101], v[158:161], v[166:169], v[98:101]
	v_mfma_f32_16x16x32_f16 v[86:89], v[94:97], v[174:177], v[86:89]
	v_mfma_f32_16x16x32_f16 v[82:85], v[158:161], v[174:177], v[82:85]
	v_mfma_f32_16x16x32_f16 v[78:81], v[94:97], v[182:185], v[78:81]
	v_mfma_f32_16x16x32_f16 v[74:77], v[158:161], v[182:185], v[74:77]
	v_mfma_f32_16x16x32_f16 v[70:73], v[94:97], v[190:193], v[70:73]
	v_mfma_f32_16x16x32_f16 v[66:69], v[158:161], v[190:193], v[66:69]
	v_mfma_f32_16x16x32_f16 v[30:33], v[194:197], v[162:165], v[30:33]
	v_mfma_f32_16x16x32_f16 v[26:29], v[202:205], v[162:165], v[26:29]
	v_mfma_f32_16x16x32_f16 v[22:25], v[194:197], v[170:173], v[22:25]
	v_mfma_f32_16x16x32_f16 v[18:21], v[202:205], v[170:173], v[18:21]
	v_mfma_f32_16x16x32_f16 v[14:17], v[194:197], v[178:181], v[14:17]
	v_mfma_f32_16x16x32_f16 v[10:13], v[202:205], v[178:181], v[10:13]
	v_mfma_f32_16x16x32_f16 v[6:9], v[194:197], v[186:189], v[6:9]
	v_mfma_f32_16x16x32_f16 v[2:5], v[202:205], v[186:189], v[2:5]
	v_mfma_f32_16x16x32_f16 v[30:33], v[198:201], v[166:169], v[30:33]
	v_mfma_f32_16x16x32_f16 v[26:29], v[220:223], v[166:169], v[26:29]
	v_mfma_f32_16x16x32_f16 v[22:25], v[198:201], v[174:177], v[22:25]
	v_mfma_f32_16x16x32_f16 v[18:21], v[220:223], v[174:177], v[18:21]
	v_mfma_f32_16x16x32_f16 v[14:17], v[198:201], v[182:185], v[14:17]
	v_mfma_f32_16x16x32_f16 v[10:13], v[220:223], v[182:185], v[10:13]
	v_mfma_f32_16x16x32_f16 v[6:9], v[198:201], v[190:193], v[6:9]
	v_mfma_f32_16x16x32_f16 v[2:5], v[220:223], v[190:193], v[2:5]
	s_barrier
; #define PG8_STAGE(bufoff, gbase, voff) do { _Pragma("unroll") for (int _i = 0; _i < 2; ++_i) \
;         __builtin_amdgcn_global_load_lds((const unsigned*)((const char*)(gbase) + (voff)[_i]), (LAS unsigned*)(lds + (bufoff) + ldsw + _i * 8192), 16, 0, 0); } while (0)
; #define PG8_LDA(dst, b, h) do { _Pragma("unroll") for (int m = 0; m < 4; ++m) _Pragma("unroll") for (int k = 0; k < 2; ++k) dst[m][k] = *(const LAS h16x8*)(lds + PG8_SA(b, h) + aoff + m * 2048 + k * 1024); } while (0)
; #define PG8_LDB(dst, b, h) do { _Pragma("unroll") for (int n = 0; n < 2; ++n) _Pragma("unroll") for (int k = 0; k < 2; ++k) dst[n][k] = *(const LAS h16x8*)(lds + PG8_SB(b, h) + boff + n * 2048 + k * 1024); } while (0)
; #define PG8_MMA(ai, bj, At, Bt_) do { __builtin_amdgcn_s_setprio(1); _Pragma("unroll") for (int m = 0; m < 4; ++m) _Pragma("unroll") for (int n = 0; n < 2; ++n) _Pragma("unroll") for (int k = 0; k < 2; ++k) \
;         acc[ai][bj][m][n] = __builtin_amdgcn_mfma_f32_16x16x32_f16(Bt_[n][k], At[m][k], acc[ai][bj][m][n], 0, 0, 0); __builtin_amdgcn_s_setprio(0); } while (0)
; #define PG8_WAIT_V(n) asm volatile("s_waitcnt vmcnt(" #n ")" ::: "memory")
; #define PG8_WAIT_L(n) asm volatile("s_waitcnt lgkmcnt(" #n ")" ::: "memory")
; #define PG8_BAR __builtin_amdgcn_s_barrier()
; #define PG8_SCHED __builtin_amdgcn_sched_barrier(0)
; template <class Epi, class AMap>
; __device__ __forceinline__ void gemm_phase(LAS unsigned char* lds, const AMap am, const int lda, const h16* Bt, const int ldb, const int M, const int N, const int K, const Epi& E) {
;     ...
;             PG8_STAGE(PG8_SB(0, 1), b2 + hstepB, voffB);
;             PG8_WAIT_V(6); PG8_BAR; PG8_MMA(1, 1, At, B1); PG8_BAR;
;             PG8_LDB(B0, 1, 0); PG8_SCHED; PG8_LDA(At, 1, 0); PG8_STAGE(PG8_SA(0, 1), a2 + hstepA, voffA);
;             PG8_WAIT_L(8); PG8_BAR; PG8_WAIT_L(0); PG8_MMA(0, 0, At, B0); PG8_BAR; PG8_SCHED;
;             PG8_LDB(B1, 1, 1); PG8_STAGE(PG8_SB(1, 0), b3, voffB);
;             PG8_BAR; PG8_WAIT_L(0); PG8_MMA(0, 1, At, B1); PG8_BAR;
	s_add_u32 s22, s26, 0x10000
	s_addc_u32 s23, s27, 0
	s_add_i32 s60, s62, s73
	v_lshl_add_u64 v[232:233], s[22:23], 0, v[0:1]
	s_mov_b32 m0, s60
	s_nop 0
	global_load_lds_dwordx4 v[232:233], off
	v_lshl_add_u64 v[232:233], s[22:23], 0, v[142:143]
	s_add_i32 m0, s60, 0x2000
	s_nop 0
	global_load_lds_dwordx4 v[232:233], off
	s_add_i32 s60, 0, 0x18000
	v_add_u32_e32 v234, s60, v155
	ds_read_b128 v[90:93], v234
	ds_read_b128 v[94:97], v234 offset:1024
	ds_read_b128 v[148:151], v234 offset:2048
	ds_read_b128 v[158:161], v234 offset:3072
	s_add_u32 s22, s48, 0x1c0000
	s_addc_u32 s23, s49, 0
	s_mov_b32 m0, s78
	v_lshl_add_u64 v[232:233], s[22:23], 0, v[138:139]
	ds_read_b128 v[162:165], v157 offset:32768
	ds_read_b128 v[166:169], v157 offset:33792
	ds_read_b128 v[170:173], v157 offset:34816
	ds_read_b128 v[174:177], v157 offset:35840
	ds_read_b128 v[178:181], v157 offset:36864
	ds_read_b128 v[182:185], v157 offset:37888
	ds_read_b128 v[186:189], v157 offset:38912
	ds_read_b128 v[190:193], v157 offset:39936
	global_load_lds_dwordx4 v[232:233], off
	v_lshl_add_u64 v[232:233], s[22:23], 0, v[140:141]
	s_mov_b32 m0, s79
	s_nop 0
	global_load_lds_dwordx4 v[232:233], off
	s_waitcnt lgkmcnt(11)
	s_add_i32 s48, 0, 0x1c000
	s_add_i32 s22, s60, s73
	v_add_u32_e32 v214, s48, v155
	v_lshl_add_u64 v[152:153], v[152:153], 0, s[92:93]
	s_mov_b32 m0, s22
	ds_read_b128 v[194:197], v214
	ds_read_b128 v[198:201], v214 offset:1024
	ds_read_b128 v[202:205], v214 offset:2048
	ds_read_b128 v[220:223], v214 offset:3072
	s_waitcnt vmcnt(8) lgkmcnt(0)
	s_barrier
	v_mfma_f32_16x16x32_f16 v[130:133], v[90:93], v[162:165], v[130:133]
	v_mfma_f32_16x16x32_f16 v[134:137], v[148:151], v[162:165], v[134:137]
	v_mfma_f32_16x16x32_f16 v[126:129], v[90:93], v[170:173], v[126:129]
	v_mfma_f32_16x16x32_f16 v[122:125], v[148:151], v[170:173], v[122:125]
	v_mfma_f32_16x16x32_f16 v[118:121], v[90:93], v[178:181], v[118:121]
	v_mfma_f32_16x16x32_f16 v[114:117], v[148:151], v[178:181], v[114:117]
	v_mfma_f32_16x16x32_f16 v[110:113], v[90:93], v[186:189], v[110:113]
	v_mfma_f32_16x16x32_f16 v[106:109], v[148:151], v[186:189], v[106:109]
	v_mfma_f32_16x16x32_f16 v[130:133], v[94:97], v[166:169], v[130:133]
	v_mfma_f32_16x16x32_f16 v[134:137], v[158:161], v[166:169], v[134:137]
	v_mfma_f32_16x16x32_f16 v[126:129], v[94:97], v[174:177], v[126:129]
	v_mfma_f32_16x16x32_f16 v[122:125], v[158:161], v[174:177], v[122:125]
	v_mfma_f32_16x16x32_f16 v[118:121], v[94:97], v[182:185], v[118:121]
	v_mfma_f32_16x16x32_f16 v[114:117], v[158:161], v[182:185], v[114:117]
	v_mfma_f32_16x16x32_f16 v[110:113], v[94:97], v[190:193], v[110:113]
	v_mfma_f32_16x16x32_f16 v[106:109], v[158:161], v[190:193], v[106:109]
	v_mfma_f32_16x16x32_f16 v[62:65], v[194:197], v[162:165], v[62:65]
	v_mfma_f32_16x16x32_f16 v[58:61], v[202:205], v[162:165], v[58:61]
	v_mfma_f32_16x16x32_f16 v[54:57], v[194:197], v[170:173], v[54:57]
	v_mfma_f32_16x16x32_f16 v[50:53], v[202:205], v[170:173], v[50:53]
	v_mfma_f32_16x16x32_f16 v[46:49], v[194:197], v[178:181], v[46:49]
	v_mfma_f32_16x16x32_f16 v[42:45], v[202:205], v[178:181], v[42:45]
	v_mfma_f32_16x16x32_f16 v[38:41], v[194:197], v[186:189], v[38:41]
	v_mfma_f32_16x16x32_f16 v[34:37], v[202:205], v[186:189], v[34:37]
	v_mfma_f32_16x16x32_f16 v[62:65], v[198:201], v[166:169], v[62:65]
	v_mfma_f32_16x16x32_f16 v[58:61], v[220:223], v[166:169], v[58:61]
	v_mfma_f32_16x16x32_f16 v[54:57], v[198:201], v[174:177], v[54:57]
	v_mfma_f32_16x16x32_f16 v[50:53], v[220:223], v[174:177], v[50:53]
	v_mfma_f32_16x16x32_f16 v[46:49], v[198:201], v[182:185], v[46:49]
	v_mfma_f32_16x16x32_f16 v[42:45], v[220:223], v[182:185], v[42:45]
	v_mfma_f32_16x16x32_f16 v[38:41], v[198:201], v[190:193], v[38:41]
	v_mfma_f32_16x16x32_f16 v[34:37], v[220:223], v[190:193], v[34:37]
	s_barrier
; #define PG8_STAGE(bufoff, gbase, voff) do { _Pragma("unroll") for (int _i = 0; _i < 2; ++_i) \
;         __builtin_amdgcn_global_load_lds((const unsigned*)((const char*)(gbase) + (voff)[_i]), (LAS unsigned*)(lds + (bufoff) + ldsw + _i * 8192), 16, 0, 0); } while (0)
; #define PG8_LDA(dst, b, h) do { _Pragma("unroll") for (int m = 0; m < 4; ++m) _Pragma("unroll") for (int k = 0; k < 2; ++k) dst[m][k] = *(const LAS h16x8*)(lds + PG8_SA(b, h) + aoff + m * 2048 + k * 1024); } while (0)
; #define PG8_MMA(ai, bj, At, Bt_) do { __builtin_amdgcn_s_setprio(1); _Pragma("unroll") for (int m = 0; m < 4; ++m) _Pragma("unroll") for (int n = 0; n < 2; ++n) _Pragma("unroll") for (int k = 0; k < 2; ++k) \
;         acc[ai][bj][m][n] = __builtin_amdgcn_mfma_f32_16x16x32_f16(Bt_[n][k], At[m][k], acc[ai][bj][m][n], 0, 0, 0); __builtin_amdgcn_s_setprio(0); } while (0)
; #define PG8_WAIT_V(n) asm volatile("s_waitcnt vmcnt(" #n ")" ::: "memory")
; #define PG8_WAIT_L(n) asm volatile("s_waitcnt lgkmcnt(" #n ")" ::: "memory")
; #define PG8_BAR __builtin_amdgcn_s_barrier()
; #define PG8_SCHED __builtin_amdgcn_sched_barrier(0)
; template <class Epi, class AMap>
; __device__ __forceinline__ void gemm_phase(LAS unsigned char* lds, const AMap am, const int lda, const h16* Bt, const int ldb, const int M, const int N, const int K, const Epi& E) {
;     ...
;             PG8_LDA(At, 1, 1); PG8_STAGE(PG8_SA(1, 0), a3, voffA);
;             PG8_BAR; PG8_WAIT_L(0); PG8_MMA(1, 0, At, B0); PG8_BAR; PG8_SCHED;
;             PG8_STAGE(PG8_SB(1, 1), b3 + hstepB, voffB);
;             PG8_WAIT_V(6); PG8_BAR; PG8_MMA(1, 1, At, B1); PG8_BAR;
;         }
;         E(acc, cur, wr, wc, fr, fq);
;         if (!has_next) break;
	global_load_lds_dwordx4 v[152:153], off
	v_lshl_add_u64 v[152:153], v[206:207], 0, s[92:93]
	s_add_i32 m0, s22, 0x2000
	s_nop 0
	global_load_lds_dwordx4 v[152:153], off
	s_mov_b32 m0, s80
	v_lshl_add_u64 v[152:153], v[212:213], 0, s[92:93]
	ds_read_b128 v[162:165], v157 offset:49152
	ds_read_b128 v[166:169], v157 offset:50176
	ds_read_b128 v[170:173], v157 offset:51200
	ds_read_b128 v[174:177], v157 offset:52224
	ds_read_b128 v[178:181], v157 offset:53248
	ds_read_b128 v[182:185], v157 offset:54272
	ds_read_b128 v[186:189], v157 offset:55296
	ds_read_b128 v[190:193], v157 offset:56320
	global_load_lds_dwordx4 v[152:153], off
	v_lshl_add_u64 v[152:153], v[224:225], 0, s[92:93]
	s_mov_b32 m0, s81
	s_nop 0
	global_load_lds_dwordx4 v[152:153], off
	s_add_u32 s22, s26, 0x10080
	s_addc_u32 s23, s27, 0
	s_add_i32 s26, s48, s73
	v_lshl_add_u64 v[232:233], s[22:23], 0, v[0:1]
	s_mov_b32 m0, s26
	s_nop 0
	global_load_lds_dwordx4 v[232:233], off
	v_lshl_add_u64 v[232:233], s[22:23], 0, v[142:143]
	s_add_i32 m0, s26, 0x2000
	s_nop 0
	global_load_lds_dwordx4 v[232:233], off
	s_add_u32 s29, s29, 0x100
	s_addc_u32 s45, s45, 0
	s_cmp_ge_i32 s51, s24
	s_mov_b64 s[22:23], s[0:1]
	s_mov_b32 s26, s51
	s_waitcnt vmcnt(8) lgkmcnt(0)
	s_barrier
	v_mfma_f32_16x16x32_f16 v[102:105], v[90:93], v[162:165], v[102:105]
	v_mfma_f32_16x16x32_f16 v[98:101], v[148:151], v[162:165], v[98:101]
	v_mfma_f32_16x16x32_f16 v[86:89], v[90:93], v[170:173], v[86:89]
	v_mfma_f32_16x16x32_f16 v[82:85], v[148:151], v[170:173], v[82:85]
	v_mfma_f32_16x16x32_f16 v[78:81], v[90:93], v[178:181], v[78:81]
	v_mfma_f32_16x16x32_f16 v[74:77], v[148:151], v[178:181], v[74:77]
	v_mfma_f32_16x16x32_f16 v[70:73], v[90:93], v[186:189], v[70:73]
	v_mfma_f32_16x16x32_f16 v[66:69], v[148:151], v[186:189], v[66:69]
	v_mfma_f32_16x16x32_f16 v[102:105], v[94:97], v[166:169], v[102:105]
	v_mfma_f32_16x16x32_f16 v[98:101], v[158:161], v[166:169], v[98:101]
	v_mfma_f32_16x16x32_f16 v[86:89], v[94:97], v[174:177], v[86:89]
	v_mfma_f32_16x16x32_f16 v[82:85], v[158:161], v[174:177], v[82:85]
	v_mfma_f32_16x16x32_f16 v[78:81], v[94:97], v[182:185], v[78:81]
	v_mfma_f32_16x16x32_f16 v[74:77], v[158:161], v[182:185], v[74:77]
	v_mfma_f32_16x16x32_f16 v[70:73], v[94:97], v[190:193], v[70:73]
	v_mfma_f32_16x16x32_f16 v[66:69], v[158:161], v[190:193], v[66:69]
	v_mfma_f32_16x16x32_f16 v[30:33], v[194:197], v[162:165], v[30:33]
	v_mfma_f32_16x16x32_f16 v[26:29], v[202:205], v[162:165], v[26:29]
	v_mfma_f32_16x16x32_f16 v[22:25], v[194:197], v[170:173], v[22:25]
	v_mfma_f32_16x16x32_f16 v[18:21], v[202:205], v[170:173], v[18:21]
	v_mfma_f32_16x16x32_f16 v[14:17], v[194:197], v[178:181], v[14:17]
	v_mfma_f32_16x16x32_f16 v[10:13], v[202:205], v[178:181], v[10:13]
	v_mfma_f32_16x16x32_f16 v[6:9], v[194:197], v[186:189], v[6:9]
	v_mfma_f32_16x16x32_f16 v[2:5], v[202:205], v[186:189], v[2:5]
	v_mfma_f32_16x16x32_f16 v[30:33], v[198:201], v[166:169], v[30:33]
	v_mfma_f32_16x16x32_f16 v[26:29], v[220:223], v[166:169], v[26:29]
	v_mfma_f32_16x16x32_f16 v[22:25], v[198:201], v[174:177], v[22:25]
	v_mfma_f32_16x16x32_f16 v[18:21], v[220:223], v[174:177], v[18:21]
	v_mfma_f32_16x16x32_f16 v[14:17], v[198:201], v[182:185], v[14:17]
	v_mfma_f32_16x16x32_f16 v[10:13], v[220:223], v[182:185], v[10:13]
	v_mfma_f32_16x16x32_f16 v[6:9], v[198:201], v[190:193], v[6:9]
	v_mfma_f32_16x16x32_f16 v[2:5], v[220:223], v[190:193], v[2:5]
	s_barrier
	s_cbranch_scc0 .LBB0_621
	s_branch .LBB0_610

; #define PG8_STAGE(bufoff, gbase, voff) do { _Pragma("unroll") for (int _i = 0; _i < 2; ++_i) \
;         __builtin_amdgcn_global_load_lds((const unsigned*)((const char*)(gbase) + (voff)[_i]), (LAS unsigned*)(lds + (bufoff) + ldsw + _i * 8192), 16, 0, 0); } while (0)
; #define PG8_LDA(dst, b, h) do { _Pragma("unroll") for (int m = 0; m < 4; ++m) _Pragma("unroll") for (int k = 0; k < 2; ++k) dst[m][k] = *(const LAS h16x8*)(lds + PG8_SA(b, h) + aoff + m * 2048 + k * 1024); } while (0)
; #define PG8_LDB(dst, b, h) do { _Pragma("unroll") for (int n = 0; n < 2; ++n) _Pragma("unroll") for (int k = 0; k < 2; ++k) dst[n][k] = *(const LAS h16x8*)(lds + PG8_SB(b, h) + boff + n * 2048 + k * 1024); } while (0)
; #define PG8_MMA(ai, bj, At, Bt_) do { __builtin_amdgcn_s_setprio(1); _Pragma("unroll") for (int m = 0; m < 4; ++m) _Pragma("unroll") for (int n = 0; n < 2; ++n) _Pragma("unroll") for (int k = 0; k < 2; ++k) \
;         acc[ai][bj][m][n] = __builtin_amdgcn_mfma_f32_16x16x32_f16(Bt_[n][k], At[m][k], acc[ai][bj][m][n], 0, 0, 0); __builtin_amdgcn_s_setprio(0); } while (0)
; #define PG8_WAIT_V(n) asm volatile("s_waitcnt vmcnt(" #n ")" ::: "memory")
; #define PG8_WAIT_L(n) asm volatile("s_waitcnt lgkmcnt(" #n ")" ::: "memory")
; template <class Epi, class AMap>
; __device__ __forceinline__ void gemm_phase(LAS unsigned char* lds, const AMap am, const int lda, const h16* Bt, const int ldb, const int M, const int N, const int K, const Epi& E) {
;     ...
;             const bool last = (t == nt - 2);
;             const char* a1 = cA + (size_t)(t + 1) * kstep;
;             const char* a2 = last ? nA : cA + (size_t)(t + 2) * kstep; const char* b2 = last ? nB : cB + (size_t)(t + 2) * kstep;
;             const char* a3 = a2 + kstep; const char* b3 = b2 + kstep;
;             PG8_LDB(B0, 0, 0); PG8_SCHED; PG8_LDA(At, 0, 0); PG8_STAGE(PG8_SA(1, 1), a1 + hstepA, voffA);
;             PG8_WAIT_L(8); PG8_BAR; PG8_WAIT_L(0); PG8_MMA(0, 0, At, B0); PG8_BAR; PG8_SCHED;
;             PG8_LDB(B1, 0, 1); PG8_STAGE(PG8_SB(0, 0), b2, voffB);
;             PG8_BAR; PG8_WAIT_L(0); PG8_MMA(0, 1, At, B1); PG8_BAR;
;             PG8_LDA(At, 0, 1); PG8_STAGE(PG8_SA(0, 0), a2, voffA);
;             PG8_BAR; PG8_WAIT_L(0); PG8_MMA(1, 0, At, B0); PG8_BAR; PG8_SCHED;
;             PG8_STAGE(PG8_SB(0, 1), b2 + hstepB, voffB);
;             PG8_WAIT_V(6); PG8_BAR; PG8_MMA(1, 1, At, B1); PG8_BAR;
.LBB0_644:
	s_add_i32 s51, s26, 2
	s_add_u32 s0, s22, 0x100
	s_addc_u32 s1, s23, 0
	s_add_i32 s60, 0, 0x10000
	v_add_u32_e32 v234, s60, v203
	ds_read_b128 v[130:133], v234
	ds_read_b128 v[134:137], v234 offset:1024
	ds_read_b128 v[138:141], v234 offset:2048
	ds_read_b128 v[152:155], v234 offset:3072
	s_cmp_eq_u32 s80, s26
	s_cselect_b32 s26, s21, s29
	s_cselect_b32 s49, s47, s1
	s_cselect_b32 s48, s46, s0
	s_cselect_b32 s27, s20, s45
	v_lshl_add_u64 v[232:233], s[22:23], 0, v[148:149]
	s_add_i32 m0, s74, 0xc000
	ds_read_b128 v[156:159], v205
	ds_read_b128 v[160:163], v205 offset:1024
	ds_read_b128 v[164:167], v205 offset:2048
	ds_read_b128 v[168:171], v205 offset:3072
	ds_read_b128 v[172:175], v205 offset:4096
	ds_read_b128 v[176:179], v205 offset:5120
	ds_read_b128 v[180:183], v205 offset:6144
	ds_read_b128 v[184:187], v205 offset:7168
	global_load_lds_dwordx4 v[232:233], off
	v_lshl_add_u64 v[232:233], s[22:23], 0, v[150:151]
	s_add_i32 m0, s74, 0xe000
	s_nop 0
	global_load_lds_dwordx4 v[232:233], off
	s_waitcnt lgkmcnt(11)
	s_add_i32 s62, 0, 0x14000
	v_add_u32_e32 v200, s62, v203
	s_add_i32 s22, s60, s71
	ds_read_b128 v[188:191], v200
	ds_read_b128 v[192:195], v200 offset:1024
	ds_read_b128 v[196:199], v200 offset:2048
	ds_read_b128 v[220:223], v200 offset:3072
	s_waitcnt vmcnt(8) lgkmcnt(0)
	s_barrier
	v_mfma_f32_16x16x32_f16 v[122:125], v[130:133], v[156:159], v[122:125]
	v_mfma_f32_16x16x32_f16 v[126:129], v[138:141], v[156:159], v[126:129]
	v_mfma_f32_16x16x32_f16 v[110:113], v[130:133], v[164:167], v[110:113]
	v_mfma_f32_16x16x32_f16 v[106:109], v[138:141], v[164:167], v[106:109]
	v_mfma_f32_16x16x32_f16 v[94:97], v[130:133], v[172:175], v[94:97]
	v_mfma_f32_16x16x32_f16 v[90:93], v[138:141], v[172:175], v[90:93]
	v_mfma_f32_16x16x32_f16 v[78:81], v[130:133], v[180:183], v[78:81]
	v_mfma_f32_16x16x32_f16 v[74:77], v[138:141], v[180:183], v[74:77]
	v_mfma_f32_16x16x32_f16 v[122:125], v[134:137], v[160:163], v[122:125]
	v_mfma_f32_16x16x32_f16 v[126:129], v[152:155], v[160:163], v[126:129]
	v_mfma_f32_16x16x32_f16 v[110:113], v[134:137], v[168:171], v[110:113]
	v_mfma_f32_16x16x32_f16 v[106:109], v[152:155], v[168:171], v[106:109]
	v_mfma_f32_16x16x32_f16 v[94:97], v[134:137], v[176:179], v[94:97]
	v_mfma_f32_16x16x32_f16 v[90:93], v[152:155], v[176:179], v[90:93]
	v_mfma_f32_16x16x32_f16 v[78:81], v[134:137], v[184:187], v[78:81]
	v_mfma_f32_16x16x32_f16 v[74:77], v[152:155], v[184:187], v[74:77]
	v_mfma_f32_16x16x32_f16 v[118:121], v[188:191], v[156:159], v[118:121]
	v_mfma_f32_16x16x32_f16 v[114:117], v[196:199], v[156:159], v[114:117]
	v_mfma_f32_16x16x32_f16 v[102:105], v[188:191], v[164:167], v[102:105]
	v_mfma_f32_16x16x32_f16 v[98:101], v[196:199], v[164:167], v[98:101]
	v_mfma_f32_16x16x32_f16 v[86:89], v[188:191], v[172:175], v[86:89]
	v_mfma_f32_16x16x32_f16 v[82:85], v[196:199], v[172:175], v[82:85]
	v_mfma_f32_16x16x32_f16 v[70:73], v[188:191], v[180:183], v[70:73]
	v_mfma_f32_16x16x32_f16 v[66:69], v[196:199], v[180:183], v[66:69]
	v_mfma_f32_16x16x32_f16 v[118:121], v[192:195], v[160:163], v[118:121]
	v_mfma_f32_16x16x32_f16 v[114:117], v[220:223], v[160:163], v[114:117]
	v_mfma_f32_16x16x32_f16 v[102:105], v[192:195], v[168:171], v[102:105]
	v_mfma_f32_16x16x32_f16 v[98:101], v[220:223], v[168:171], v[98:101]
	v_mfma_f32_16x16x32_f16 v[86:89], v[192:195], v[176:179], v[86:89]
	v_mfma_f32_16x16x32_f16 v[82:85], v[220:223], v[176:179], v[82:85]
	v_mfma_f32_16x16x32_f16 v[70:73], v[192:195], v[184:187], v[70:73]
	v_mfma_f32_16x16x32_f16 v[66:69], v[220:223], v[184:187], v[66:69]
	s_barrier
	v_lshl_add_u64 v[200:201], s[26:27], 0, v[0:1]
	s_mov_b32 m0, s22
	v_lshl_add_u64 v[206:207], s[26:27], 0, v[146:147]
	global_load_lds_dwordx4 v[200:201], off
	s_add_i32 m0, s22, 0x2000
	s_nop 0
	global_load_lds_dwordx4 v[206:207], off
	s_mov_b32 m0, s74
	v_lshl_add_u64 v[212:213], s[48:49], 0, v[142:143]
	ds_read_b128 v[156:159], v205 offset:16384
	ds_read_b128 v[160:163], v205 offset:17408
	ds_read_b128 v[164:167], v205 offset:18432
	ds_read_b128 v[168:171], v205 offset:19456
	ds_read_b128 v[172:175], v205 offset:20480
	ds_read_b128 v[176:179], v205 offset:21504
	ds_read_b128 v[180:183], v205 offset:22528
	ds_read_b128 v[184:187], v205 offset:23552
	global_load_lds_dwordx4 v[212:213], off
	v_lshl_add_u64 v[224:225], s[48:49], 0, v[144:145]
	s_mov_b32 m0, s75
	s_nop 0
	global_load_lds_dwordx4 v[224:225], off
	s_waitcnt vmcnt(6) lgkmcnt(0)
	s_barrier
	v_mfma_f32_16x16x32_f16 v[62:65], v[130:133], v[156:159], v[62:65]
	v_mfma_f32_16x16x32_f16 v[58:61], v[138:141], v[156:159], v[58:61]
	v_mfma_f32_16x16x32_f16 v[46:49], v[130:133], v[164:167], v[46:49]
	v_mfma_f32_16x16x32_f16 v[42:45], v[138:141], v[164:167], v[42:45]
	v_mfma_f32_16x16x32_f16 v[30:33], v[130:133], v[172:175], v[30:33]
	v_mfma_f32_16x16x32_f16 v[26:29], v[138:141], v[172:175], v[26:29]
	v_mfma_f32_16x16x32_f16 v[14:17], v[130:133], v[180:183], v[14:17]
	v_mfma_f32_16x16x32_f16 v[10:13], v[138:141], v[180:183], v[10:13]
	v_mfma_f32_16x16x32_f16 v[62:65], v[134:137], v[160:163], v[62:65]
	v_mfma_f32_16x16x32_f16 v[58:61], v[152:155], v[160:163], v[58:61]
	v_mfma_f32_16x16x32_f16 v[46:49], v[134:137], v[168:171], v[46:49]
	v_mfma_f32_16x16x32_f16 v[42:45], v[152:155], v[168:171], v[42:45]
	v_mfma_f32_16x16x32_f16 v[30:33], v[134:137], v[176:179], v[30:33]
	v_mfma_f32_16x16x32_f16 v[26:29], v[152:155], v[176:179], v[26:29]
	v_mfma_f32_16x16x32_f16 v[14:17], v[134:137], v[184:187], v[14:17]
	v_mfma_f32_16x16x32_f16 v[10:13], v[152:155], v[184:187], v[10:13]
	v_mfma_f32_16x16x32_f16 v[54:57], v[188:191], v[156:159], v[54:57]
	v_mfma_f32_16x16x32_f16 v[50:53], v[196:199], v[156:159], v[50:53]
	v_mfma_f32_16x16x32_f16 v[38:41], v[188:191], v[164:167], v[38:41]
	v_mfma_f32_16x16x32_f16 v[34:37], v[196:199], v[164:167], v[34:37]
	v_mfma_f32_16x16x32_f16 v[22:25], v[188:191], v[172:175], v[22:25]
	v_mfma_f32_16x16x32_f16 v[18:21], v[196:199], v[172:175], v[18:21]
	v_mfma_f32_16x16x32_f16 v[6:9], v[188:191], v[180:183], v[6:9]
	v_mfma_f32_16x16x32_f16 v[2:5], v[196:199], v[180:183], v[2:5]
	v_mfma_f32_16x16x32_f16 v[54:57], v[192:195], v[160:163], v[54:57]
	v_mfma_f32_16x16x32_f16 v[50:53], v[220:223], v[160:163], v[50:53]
	v_mfma_f32_16x16x32_f16 v[38:41], v[192:195], v[168:171], v[38:41]
	v_mfma_f32_16x16x32_f16 v[34:37], v[220:223], v[168:171], v[34:37]
	v_mfma_f32_16x16x32_f16 v[22:25], v[192:195], v[176:179], v[22:25]
	v_mfma_f32_16x16x32_f16 v[18:21], v[220:223], v[176:179], v[18:21]
	v_mfma_f32_16x16x32_f16 v[6:9], v[192:195], v[184:187], v[6:9]
	v_mfma_f32_16x16x32_f16 v[2:5], v[220:223], v[184:187], v[2:5]
	s_barrier
; #define PG8_STAGE(bufoff, gbase, voff) do { _Pragma("unroll") for (int _i = 0; _i < 2; ++_i) \
;         __builtin_amdgcn_global_load_lds((const unsigned*)((const char*)(gbase) + (voff)[_i]), (LAS unsigned*)(lds + (bufoff) + ldsw + _i * 8192), 16, 0, 0); } while (0)
; #define PG8_LDA(dst, b, h) do { _Pragma("unroll") for (int m = 0; m < 4; ++m) _Pragma("unroll") for (int k = 0; k < 2; ++k) dst[m][k] = *(const LAS h16x8*)(lds + PG8_SA(b, h) + aoff + m * 2048 + k * 1024); } while (0)
; #define PG8_LDB(dst, b, h) do { _Pragma("unroll") for (int n = 0; n < 2; ++n) _Pragma("unroll") for (int k = 0; k < 2; ++k) dst[n][k] = *(const LAS h16x8*)(lds + PG8_SB(b, h) + boff + n * 2048 + k * 1024); } while (0)
; #define PG8_MMA(ai, bj, At, Bt_) do { __builtin_amdgcn_s_setprio(1); _Pragma("unroll") for (int m = 0; m < 4; ++m) _Pragma("unroll") for (int n = 0; n < 2; ++n) _Pragma("unroll") for (int k = 0; k < 2; ++k) \
;         acc[ai][bj][m][n] = __builtin_amdgcn_mfma_f32_16x16x32_f16(Bt_[n][k], At[m][k], acc[ai][bj][m][n], 0, 0, 0); __builtin_amdgcn_s_setprio(0); } while (0)
; #define PG8_WAIT_V(n) asm volatile("s_waitcnt vmcnt(" #n ")" ::: "memory")
; #define PG8_WAIT_L(n) asm volatile("s_waitcnt lgkmcnt(" #n ")" ::: "memory")
; #define PG8_BAR __builtin_amdgcn_s_barrier()
; #define PG8_SCHED __builtin_amdgcn_sched_barrier(0)
; template <class Epi, class AMap>
; __device__ __forceinline__ void gemm_phase(LAS unsigned char* lds, const AMap am, const int lda, const h16* Bt, const int ldb, const int M, const int N, const int K, const Epi& E) {
;     ...
;             PG8_STAGE(PG8_SB(0, 1), b2 + hstepB, voffB);
;             PG8_WAIT_V(6); PG8_BAR; PG8_MMA(1, 1, At, B1); PG8_BAR;
;             PG8_LDB(B0, 1, 0); PG8_SCHED; PG8_LDA(At, 1, 0); PG8_STAGE(PG8_SA(0, 1), a2 + hstepA, voffA);
;             PG8_WAIT_L(8); PG8_BAR; PG8_WAIT_L(0); PG8_MMA(0, 0, At, B0); PG8_BAR; PG8_SCHED;
;             PG8_LDB(B1, 1, 1); PG8_STAGE(PG8_SB(1, 0), b3, voffB);
;             PG8_BAR; PG8_WAIT_L(0); PG8_MMA(0, 1, At, B1); PG8_BAR;
	s_add_u32 s22, s26, 0x10000
	s_addc_u32 s23, s27, 0
	s_add_i32 s60, s62, s71
	v_lshl_add_u64 v[232:233], s[22:23], 0, v[0:1]
	s_mov_b32 m0, s60
	s_nop 0
	global_load_lds_dwordx4 v[232:233], off
	v_lshl_add_u64 v[232:233], s[22:23], 0, v[146:147]
	s_add_i32 m0, s60, 0x2000
	s_nop 0
	global_load_lds_dwordx4 v[232:233], off
	s_add_i32 s60, 0, 0x18000
	v_add_u32_e32 v234, s60, v203
	ds_read_b128 v[130:133], v234
	ds_read_b128 v[134:137], v234 offset:1024
	ds_read_b128 v[138:141], v234 offset:2048
	ds_read_b128 v[152:155], v234 offset:3072
	s_add_u32 s22, s48, 0x1c0000
	s_addc_u32 s23, s49, 0
	s_mov_b32 m0, s76
	v_lshl_add_u64 v[232:233], s[22:23], 0, v[142:143]
	ds_read_b128 v[156:159], v205 offset:32768
	ds_read_b128 v[160:163], v205 offset:33792
	ds_read_b128 v[164:167], v205 offset:34816
	ds_read_b128 v[168:171], v205 offset:35840
	ds_read_b128 v[172:175], v205 offset:36864
	ds_read_b128 v[176:179], v205 offset:37888
	ds_read_b128 v[180:183], v205 offset:38912
	ds_read_b128 v[184:187], v205 offset:39936
	global_load_lds_dwordx4 v[232:233], off
	v_lshl_add_u64 v[232:233], s[22:23], 0, v[144:145]
	s_mov_b32 m0, s77
	s_nop 0
	global_load_lds_dwordx4 v[232:233], off
	s_waitcnt lgkmcnt(11)
	s_add_i32 s48, 0, 0x1c000
	s_add_i32 s22, s60, s71
	v_add_u32_e32 v214, s48, v203
	v_lshl_add_u64 v[200:201], v[200:201], 0, s[92:93]
	s_mov_b32 m0, s22
	ds_read_b128 v[188:191], v214
	ds_read_b128 v[192:195], v214 offset:1024
	ds_read_b128 v[196:199], v214 offset:2048
	ds_read_b128 v[220:223], v214 offset:3072
	s_waitcnt vmcnt(8) lgkmcnt(0)
	s_barrier
	v_mfma_f32_16x16x32_f16 v[122:125], v[130:133], v[156:159], v[122:125]
	v_mfma_f32_16x16x32_f16 v[126:129], v[138:141], v[156:159], v[126:129]
	v_mfma_f32_16x16x32_f16 v[110:113], v[130:133], v[164:167], v[110:113]
	v_mfma_f32_16x16x32_f16 v[106:109], v[138:141], v[164:167], v[106:109]
	v_mfma_f32_16x16x32_f16 v[94:97], v[130:133], v[172:175], v[94:97]
	v_mfma_f32_16x16x32_f16 v[90:93], v[138:141], v[172:175], v[90:93]
	v_mfma_f32_16x16x32_f16 v[78:81], v[130:133], v[180:183], v[78:81]
	v_mfma_f32_16x16x32_f16 v[74:77], v[138:141], v[180:183], v[74:77]
	v_mfma_f32_16x16x32_f16 v[122:125], v[134:137], v[160:163], v[122:125]
	v_mfma_f32_16x16x32_f16 v[126:129], v[152:155], v[160:163], v[126:129]
	v_mfma_f32_16x16x32_f16 v[110:113], v[134:137], v[168:171], v[110:113]
	v_mfma_f32_16x16x32_f16 v[106:109], v[152:155], v[168:171], v[106:109]
	v_mfma_f32_16x16x32_f16 v[94:97], v[134:137], v[176:179], v[94:97]
	v_mfma_f32_16x16x32_f16 v[90:93], v[152:155], v[176:179], v[90:93]
	v_mfma_f32_16x16x32_f16 v[78:81], v[134:137], v[184:187], v[78:81]
	v_mfma_f32_16x16x32_f16 v[74:77], v[152:155], v[184:187], v[74:77]
	v_mfma_f32_16x16x32_f16 v[118:121], v[188:191], v[156:159], v[118:121]
	v_mfma_f32_16x16x32_f16 v[114:117], v[196:199], v[156:159], v[114:117]
	v_mfma_f32_16x16x32_f16 v[102:105], v[188:191], v[164:167], v[102:105]
	v_mfma_f32_16x16x32_f16 v[98:101], v[196:199], v[164:167], v[98:101]
	v_mfma_f32_16x16x32_f16 v[86:89], v[188:191], v[172:175], v[86:89]
	v_mfma_f32_16x16x32_f16 v[82:85], v[196:199], v[172:175], v[82:85]
	v_mfma_f32_16x16x32_f16 v[70:73], v[188:191], v[180:183], v[70:73]
	v_mfma_f32_16x16x32_f16 v[66:69], v[196:199], v[180:183], v[66:69]
	v_mfma_f32_16x16x32_f16 v[118:121], v[192:195], v[160:163], v[118:121]
	v_mfma_f32_16x16x32_f16 v[114:117], v[220:223], v[160:163], v[114:117]
	v_mfma_f32_16x16x32_f16 v[102:105], v[192:195], v[168:171], v[102:105]
	v_mfma_f32_16x16x32_f16 v[98:101], v[220:223], v[168:171], v[98:101]
	v_mfma_f32_16x16x32_f16 v[86:89], v[192:195], v[176:179], v[86:89]
	v_mfma_f32_16x16x32_f16 v[82:85], v[220:223], v[176:179], v[82:85]
	v_mfma_f32_16x16x32_f16 v[70:73], v[192:195], v[184:187], v[70:73]
	v_mfma_f32_16x16x32_f16 v[66:69], v[220:223], v[184:187], v[66:69]
	s_barrier
; #define PG8_STAGE(bufoff, gbase, voff) do { _Pragma("unroll") for (int _i = 0; _i < 2; ++_i) \
;         __builtin_amdgcn_global_load_lds((const unsigned*)((const char*)(gbase) + (voff)[_i]), (LAS unsigned*)(lds + (bufoff) + ldsw + _i * 8192), 16, 0, 0); } while (0)
; #define PG8_LDA(dst, b, h) do { _Pragma("unroll") for (int m = 0; m < 4; ++m) _Pragma("unroll") for (int k = 0; k < 2; ++k) dst[m][k] = *(const LAS h16x8*)(lds + PG8_SA(b, h) + aoff + m * 2048 + k * 1024); } while (0)
; #define PG8_MMA(ai, bj, At, Bt_) do { __builtin_amdgcn_s_setprio(1); _Pragma("unroll") for (int m = 0; m < 4; ++m) _Pragma("unroll") for (int n = 0; n < 2; ++n) _Pragma("unroll") for (int k = 0; k < 2; ++k) \
;         acc[ai][bj][m][n] = __builtin_amdgcn_mfma_f32_16x16x32_f16(Bt_[n][k], At[m][k], acc[ai][bj][m][n], 0, 0, 0); __builtin_amdgcn_s_setprio(0); } while (0)
; #define PG8_WAIT_V(n) asm volatile("s_waitcnt vmcnt(" #n ")" ::: "memory")
; #define PG8_WAIT_L(n) asm volatile("s_waitcnt lgkmcnt(" #n ")" ::: "memory")
; #define PG8_BAR __builtin_amdgcn_s_barrier()
; #define PG8_SCHED __builtin_amdgcn_sched_barrier(0)
; template <class Epi, class AMap>
; __device__ __forceinline__ void gemm_phase(LAS unsigned char* lds, const AMap am, const int lda, const h16* Bt, const int ldb, const int M, const int N, const int K, const Epi& E) {
;     ...
;             PG8_LDA(At, 1, 1); PG8_STAGE(PG8_SA(1, 0), a3, voffA);
;             PG8_BAR; PG8_WAIT_L(0); PG8_MMA(1, 0, At, B0); PG8_BAR; PG8_SCHED;
;             PG8_STAGE(PG8_SB(1, 1), b3 + hstepB, voffB);
;             PG8_WAIT_V(6); PG8_BAR; PG8_MMA(1, 1, At, B1); PG8_BAR;
;         }
;         E(acc, cur, wr, wc, fr, fq);
;         if (!has_next) break;
	global_load_lds_dwordx4 v[200:201], off
	v_lshl_add_u64 v[200:201], v[206:207], 0, s[92:93]
	s_add_i32 m0, s22, 0x2000
	s_nop 0
	global_load_lds_dwordx4 v[200:201], off
	s_mov_b32 m0, s78
	v_lshl_add_u64 v[200:201], v[212:213], 0, s[92:93]
	ds_read_b128 v[156:159], v205 offset:49152
	ds_read_b128 v[160:163], v205 offset:50176
	ds_read_b128 v[164:167], v205 offset:51200
	ds_read_b128 v[168:171], v205 offset:52224
	ds_read_b128 v[172:175], v205 offset:53248
	ds_read_b128 v[176:179], v205 offset:54272
	ds_read_b128 v[180:183], v205 offset:55296
	ds_read_b128 v[184:187], v205 offset:56320
	global_load_lds_dwordx4 v[200:201], off
	v_lshl_add_u64 v[200:201], v[224:225], 0, s[92:93]
	s_mov_b32 m0, s79
	s_nop 0
	global_load_lds_dwordx4 v[200:201], off
	s_add_u32 s22, s26, 0x10080
	s_addc_u32 s23, s27, 0
	s_add_i32 s26, s48, s71
	v_lshl_add_u64 v[232:233], s[22:23], 0, v[0:1]
	s_mov_b32 m0, s26
	s_nop 0
	global_load_lds_dwordx4 v[232:233], off
	v_lshl_add_u64 v[232:233], s[22:23], 0, v[146:147]
	s_add_i32 m0, s26, 0x2000
	s_nop 0
	global_load_lds_dwordx4 v[232:233], off
	s_add_u32 s29, s29, 0x100
	s_addc_u32 s45, s45, 0
	s_cmp_ge_i32 s51, s24
	s_mov_b64 s[22:23], s[0:1]
	s_mov_b32 s26, s51
	s_waitcnt vmcnt(8) lgkmcnt(0)
	s_barrier
	v_mfma_f32_16x16x32_f16 v[62:65], v[130:133], v[156:159], v[62:65]
	v_mfma_f32_16x16x32_f16 v[58:61], v[138:141], v[156:159], v[58:61]
	v_mfma_f32_16x16x32_f16 v[46:49], v[130:133], v[164:167], v[46:49]
	v_mfma_f32_16x16x32_f16 v[42:45], v[138:141], v[164:167], v[42:45]
	v_mfma_f32_16x16x32_f16 v[30:33], v[130:133], v[172:175], v[30:33]
	v_mfma_f32_16x16x32_f16 v[26:29], v[138:141], v[172:175], v[26:29]
	v_mfma_f32_16x16x32_f16 v[14:17], v[130:133], v[180:183], v[14:17]
	v_mfma_f32_16x16x32_f16 v[10:13], v[138:141], v[180:183], v[10:13]
	v_mfma_f32_16x16x32_f16 v[62:65], v[134:137], v[160:163], v[62:65]
	v_mfma_f32_16x16x32_f16 v[58:61], v[152:155], v[160:163], v[58:61]
	v_mfma_f32_16x16x32_f16 v[46:49], v[134:137], v[168:171], v[46:49]
	v_mfma_f32_16x16x32_f16 v[42:45], v[152:155], v[168:171], v[42:45]
	v_mfma_f32_16x16x32_f16 v[30:33], v[134:137], v[176:179], v[30:33]
	v_mfma_f32_16x16x32_f16 v[26:29], v[152:155], v[176:179], v[26:29]
	v_mfma_f32_16x16x32_f16 v[14:17], v[134:137], v[184:187], v[14:17]
	v_mfma_f32_16x16x32_f16 v[10:13], v[152:155], v[184:187], v[10:13]
	v_mfma_f32_16x16x32_f16 v[54:57], v[188:191], v[156:159], v[54:57]
	v_mfma_f32_16x16x32_f16 v[50:53], v[196:199], v[156:159], v[50:53]
	v_mfma_f32_16x16x32_f16 v[38:41], v[188:191], v[164:167], v[38:41]
	v_mfma_f32_16x16x32_f16 v[34:37], v[196:199], v[164:167], v[34:37]
	v_mfma_f32_16x16x32_f16 v[22:25], v[188:191], v[172:175], v[22:25]
	v_mfma_f32_16x16x32_f16 v[18:21], v[196:199], v[172:175], v[18:21]
	v_mfma_f32_16x16x32_f16 v[6:9], v[188:191], v[180:183], v[6:9]
	v_mfma_f32_16x16x32_f16 v[2:5], v[196:199], v[180:183], v[2:5]
	v_mfma_f32_16x16x32_f16 v[54:57], v[192:195], v[160:163], v[54:57]
	v_mfma_f32_16x16x32_f16 v[50:53], v[220:223], v[160:163], v[50:53]
	v_mfma_f32_16x16x32_f16 v[38:41], v[192:195], v[168:171], v[38:41]
	v_mfma_f32_16x16x32_f16 v[34:37], v[220:223], v[168:171], v[34:37]
	v_mfma_f32_16x16x32_f16 v[22:25], v[192:195], v[176:179], v[22:25]
	v_mfma_f32_16x16x32_f16 v[18:21], v[220:223], v[176:179], v[18:21]
	v_mfma_f32_16x16x32_f16 v[6:9], v[192:195], v[184:187], v[6:9]
	v_mfma_f32_16x16x32_f16 v[2:5], v[220:223], v[184:187], v[2:5]
	s_barrier
	s_cbranch_scc0 .LBB0_644
	s_branch .LBB0_633

; #define PG8_STAGE(bufoff, gbase, voff) do { _Pragma("unroll") for (int _i = 0; _i < 2; ++_i) \
;         __builtin_amdgcn_global_load_lds((const unsigned*)((const char*)(gbase) + (voff)[_i]), (LAS unsigned*)(lds + (bufoff) + ldsw + _i * 8192), 16, 0, 0); } while (0)
; #define PG8_LDA(dst, b, h) do { _Pragma("unroll") for (int m = 0; m < 4; ++m) _Pragma("unroll") for (int k = 0; k < 2; ++k) dst[m][k] = *(const LAS h16x8*)(lds + PG8_SA(b, h) + aoff + m * 2048 + k * 1024); } while (0)
; #define PG8_LDB(dst, b, h) do { _Pragma("unroll") for (int n = 0; n < 2; ++n) _Pragma("unroll") for (int k = 0; k < 2; ++k) dst[n][k] = *(const LAS h16x8*)(lds + PG8_SB(b, h) + boff + n * 2048 + k * 1024); } while (0)
; #define PG8_MMA(ai, bj, At, Bt_) do { __builtin_amdgcn_s_setprio(1); _Pragma("unroll") for (int m = 0; m < 4; ++m) _Pragma("unroll") for (int n = 0; n < 2; ++n) _Pragma("unroll") for (int k = 0; k < 2; ++k) \
;         acc[ai][bj][m][n] = __builtin_amdgcn_mfma_f32_16x16x32_f16(Bt_[n][k], At[m][k], acc[ai][bj][m][n], 0, 0, 0); __builtin_amdgcn_s_setprio(0); } while (0)
; #define PG8_WAIT_V(n) asm volatile("s_waitcnt vmcnt(" #n ")" ::: "memory")
; #define PG8_WAIT_L(n) asm volatile("s_waitcnt lgkmcnt(" #n ")" ::: "memory")
; template <class Epi, class AMap>
; __device__ __forceinline__ void gemm_phase(LAS unsigned char* lds, const AMap am, const int lda, const h16* Bt, const int ldb, const int M, const int N, const int K, const Epi& E) {
;     ...
;             const bool last = (t == nt - 2);
;             const char* a1 = cA + (size_t)(t + 1) * kstep;
;             const char* a2 = last ? nA : cA + (size_t)(t + 2) * kstep; const char* b2 = last ? nB : cB + (size_t)(t + 2) * kstep;
;             const char* a3 = a2 + kstep; const char* b3 = b2 + kstep;
;             PG8_LDB(B0, 0, 0); PG8_SCHED; PG8_LDA(At, 0, 0); PG8_STAGE(PG8_SA(1, 1), a1 + hstepA, voffA);
;             PG8_WAIT_L(8); PG8_BAR; PG8_WAIT_L(0); PG8_MMA(0, 0, At, B0); PG8_BAR; PG8_SCHED;
;             PG8_LDB(B1, 0, 1); PG8_STAGE(PG8_SB(0, 0), b2, voffB);
;             PG8_BAR; PG8_WAIT_L(0); PG8_MMA(0, 1, At, B1); PG8_BAR;
;             PG8_LDA(At, 0, 1); PG8_STAGE(PG8_SA(0, 0), a2, voffA);
;             PG8_BAR; PG8_WAIT_L(0); PG8_MMA(1, 0, At, B0); PG8_BAR; PG8_SCHED;
;             PG8_STAGE(PG8_SB(0, 1), b2 + hstepB, voffB);
;             PG8_WAIT_V(6); PG8_BAR; PG8_MMA(1, 1, At, B1); PG8_BAR;
.LBB0_692:
	s_add_i32 s51, s26, 2
	s_add_u32 s0, s22, 0x100
	s_addc_u32 s1, s23, 0
	s_add_i32 s60, 0, 0x10000
	v_add_u32_e32 v234, s60, v175
	ds_read_b128 v[82:85], v234
	ds_read_b128 v[86:89], v234 offset:1024
	ds_read_b128 v[138:141], v234 offset:2048
	ds_read_b128 v[142:145], v234 offset:3072
	s_cmp_eq_u32 s61, s26
	s_cselect_b32 s26, s21, s29
	s_cselect_b32 s49, s47, s1
	s_cselect_b32 s48, s46, s0
	s_cselect_b32 s27, s20, s45
	v_lshl_add_u64 v[172:173], s[22:23], 0, v[152:153]
	s_add_i32 m0, s74, 0xc000
	ds_read_b128 v[156:159], v177
	ds_read_b128 v[160:163], v177 offset:1024
	ds_read_b128 v[164:167], v177 offset:2048
	ds_read_b128 v[168:171], v177 offset:3072
	ds_read_b128 v[178:181], v177 offset:4096
	ds_read_b128 v[182:185], v177 offset:5120
	ds_read_b128 v[186:189], v177 offset:6144
	ds_read_b128 v[190:193], v177 offset:7168
	global_load_lds_dwordx4 v[172:173], off
	v_lshl_add_u64 v[172:173], s[22:23], 0, v[154:155]
	s_add_i32 m0, s74, 0xe000
	s_nop 0
	global_load_lds_dwordx4 v[172:173], off
	s_waitcnt lgkmcnt(11)
	s_add_i32 s62, 0, 0x14000
	v_add_u32_e32 v172, s62, v175
	s_add_i32 s22, s60, s71
	ds_read_b128 v[194:197], v172
	ds_read_b128 v[198:201], v172 offset:1024
	ds_read_b128 v[202:205], v172 offset:2048
	ds_read_b128 v[220:223], v172 offset:3072
	s_waitcnt vmcnt(8) lgkmcnt(0)
	s_barrier
	v_mfma_f32_16x16x32_f16 v[134:137], v[82:85], v[156:159], v[134:137]
	v_mfma_f32_16x16x32_f16 v[130:133], v[138:141], v[156:159], v[130:133]
	v_mfma_f32_16x16x32_f16 v[126:129], v[82:85], v[164:167], v[126:129]
	v_mfma_f32_16x16x32_f16 v[122:125], v[138:141], v[164:167], v[122:125]
	v_mfma_f32_16x16x32_f16 v[118:121], v[82:85], v[178:181], v[118:121]
	v_mfma_f32_16x16x32_f16 v[114:117], v[138:141], v[178:181], v[114:117]
	v_mfma_f32_16x16x32_f16 v[110:113], v[82:85], v[186:189], v[110:113]
	v_mfma_f32_16x16x32_f16 v[106:109], v[138:141], v[186:189], v[106:109]
	v_mfma_f32_16x16x32_f16 v[134:137], v[86:89], v[160:163], v[134:137]
	v_mfma_f32_16x16x32_f16 v[130:133], v[142:145], v[160:163], v[130:133]
	v_mfma_f32_16x16x32_f16 v[126:129], v[86:89], v[168:171], v[126:129]
	v_mfma_f32_16x16x32_f16 v[122:125], v[142:145], v[168:171], v[122:125]
	v_mfma_f32_16x16x32_f16 v[118:121], v[86:89], v[182:185], v[118:121]
	v_mfma_f32_16x16x32_f16 v[114:117], v[142:145], v[182:185], v[114:117]
	v_mfma_f32_16x16x32_f16 v[110:113], v[86:89], v[190:193], v[110:113]
	v_mfma_f32_16x16x32_f16 v[106:109], v[142:145], v[190:193], v[106:109]
	v_mfma_f32_16x16x32_f16 v[62:65], v[194:197], v[156:159], v[62:65]
	v_mfma_f32_16x16x32_f16 v[58:61], v[202:205], v[156:159], v[58:61]
	v_mfma_f32_16x16x32_f16 v[54:57], v[194:197], v[164:167], v[54:57]
	v_mfma_f32_16x16x32_f16 v[50:53], v[202:205], v[164:167], v[50:53]
	v_mfma_f32_16x16x32_f16 v[46:49], v[194:197], v[178:181], v[46:49]
	v_mfma_f32_16x16x32_f16 v[42:45], v[202:205], v[178:181], v[42:45]
	v_mfma_f32_16x16x32_f16 v[38:41], v[194:197], v[186:189], v[38:41]
	v_mfma_f32_16x16x32_f16 v[34:37], v[202:205], v[186:189], v[34:37]
	v_mfma_f32_16x16x32_f16 v[62:65], v[198:201], v[160:163], v[62:65]
	v_mfma_f32_16x16x32_f16 v[58:61], v[220:223], v[160:163], v[58:61]
	v_mfma_f32_16x16x32_f16 v[54:57], v[198:201], v[168:171], v[54:57]
	v_mfma_f32_16x16x32_f16 v[50:53], v[220:223], v[168:171], v[50:53]
	v_mfma_f32_16x16x32_f16 v[46:49], v[198:201], v[182:185], v[46:49]
	v_mfma_f32_16x16x32_f16 v[42:45], v[220:223], v[182:185], v[42:45]
	v_mfma_f32_16x16x32_f16 v[38:41], v[198:201], v[190:193], v[38:41]
	v_mfma_f32_16x16x32_f16 v[34:37], v[220:223], v[190:193], v[34:37]
	s_barrier
	v_lshl_add_u64 v[172:173], s[26:27], 0, v[0:1]
	s_mov_b32 m0, s22
	v_lshl_add_u64 v[206:207], s[26:27], 0, v[150:151]
	global_load_lds_dwordx4 v[172:173], off
	s_add_i32 m0, s22, 0x2000
	s_nop 0
	global_load_lds_dwordx4 v[206:207], off
	s_mov_b32 m0, s74
	v_lshl_add_u64 v[212:213], s[48:49], 0, v[146:147]
	ds_read_b128 v[156:159], v177 offset:16384
	ds_read_b128 v[160:163], v177 offset:17408
	ds_read_b128 v[164:167], v177 offset:18432
	ds_read_b128 v[168:171], v177 offset:19456
	ds_read_b128 v[178:181], v177 offset:20480
	ds_read_b128 v[182:185], v177 offset:21504
	ds_read_b128 v[186:189], v177 offset:22528
	ds_read_b128 v[190:193], v177 offset:23552
	global_load_lds_dwordx4 v[212:213], off
	v_lshl_add_u64 v[224:225], s[48:49], 0, v[148:149]
	s_mov_b32 m0, s75
	s_nop 0
	global_load_lds_dwordx4 v[224:225], off
	s_waitcnt vmcnt(6) lgkmcnt(0)
	s_barrier
	v_mfma_f32_16x16x32_f16 v[102:105], v[82:85], v[156:159], v[102:105]
	v_mfma_f32_16x16x32_f16 v[98:101], v[138:141], v[156:159], v[98:101]
	v_mfma_f32_16x16x32_f16 v[94:97], v[82:85], v[164:167], v[94:97]
	v_mfma_f32_16x16x32_f16 v[90:93], v[138:141], v[164:167], v[90:93]
	v_mfma_f32_16x16x32_f16 v[78:81], v[82:85], v[178:181], v[78:81]
	v_mfma_f32_16x16x32_f16 v[74:77], v[138:141], v[178:181], v[74:77]
	v_mfma_f32_16x16x32_f16 v[70:73], v[82:85], v[186:189], v[70:73]
	v_mfma_f32_16x16x32_f16 v[66:69], v[138:141], v[186:189], v[66:69]
	v_mfma_f32_16x16x32_f16 v[102:105], v[86:89], v[160:163], v[102:105]
	v_mfma_f32_16x16x32_f16 v[98:101], v[142:145], v[160:163], v[98:101]
	v_mfma_f32_16x16x32_f16 v[94:97], v[86:89], v[168:171], v[94:97]
	v_mfma_f32_16x16x32_f16 v[90:93], v[142:145], v[168:171], v[90:93]
	v_mfma_f32_16x16x32_f16 v[78:81], v[86:89], v[182:185], v[78:81]
	v_mfma_f32_16x16x32_f16 v[74:77], v[142:145], v[182:185], v[74:77]
	v_mfma_f32_16x16x32_f16 v[70:73], v[86:89], v[190:193], v[70:73]
	v_mfma_f32_16x16x32_f16 v[66:69], v[142:145], v[190:193], v[66:69]
	v_mfma_f32_16x16x32_f16 v[30:33], v[194:197], v[156:159], v[30:33]
	v_mfma_f32_16x16x32_f16 v[26:29], v[202:205], v[156:159], v[26:29]
	v_mfma_f32_16x16x32_f16 v[22:25], v[194:197], v[164:167], v[22:25]
	v_mfma_f32_16x16x32_f16 v[18:21], v[202:205], v[164:167], v[18:21]
	v_mfma_f32_16x16x32_f16 v[14:17], v[194:197], v[178:181], v[14:17]
	v_mfma_f32_16x16x32_f16 v[10:13], v[202:205], v[178:181], v[10:13]
	v_mfma_f32_16x16x32_f16 v[6:9], v[194:197], v[186:189], v[6:9]
	v_mfma_f32_16x16x32_f16 v[2:5], v[202:205], v[186:189], v[2:5]
	v_mfma_f32_16x16x32_f16 v[30:33], v[198:201], v[160:163], v[30:33]
	v_mfma_f32_16x16x32_f16 v[26:29], v[220:223], v[160:163], v[26:29]
	v_mfma_f32_16x16x32_f16 v[22:25], v[198:201], v[168:171], v[22:25]
	v_mfma_f32_16x16x32_f16 v[18:21], v[220:223], v[168:171], v[18:21]
	v_mfma_f32_16x16x32_f16 v[14:17], v[198:201], v[182:185], v[14:17]
	v_mfma_f32_16x16x32_f16 v[10:13], v[220:223], v[182:185], v[10:13]
	v_mfma_f32_16x16x32_f16 v[6:9], v[198:201], v[190:193], v[6:9]
	v_mfma_f32_16x16x32_f16 v[2:5], v[220:223], v[190:193], v[2:5]
	s_barrier
; #define PG8_STAGE(bufoff, gbase, voff) do { _Pragma("unroll") for (int _i = 0; _i < 2; ++_i) \
;         __builtin_amdgcn_global_load_lds((const unsigned*)((const char*)(gbase) + (voff)[_i]), (LAS unsigned*)(lds + (bufoff) + ldsw + _i * 8192), 16, 0, 0); } while (0)
; #define PG8_LDA(dst, b, h) do { _Pragma("unroll") for (int m = 0; m < 4; ++m) _Pragma("unroll") for (int k = 0; k < 2; ++k) dst[m][k] = *(const LAS h16x8*)(lds + PG8_SA(b, h) + aoff + m * 2048 + k * 1024); } while (0)
; #define PG8_LDB(dst, b, h) do { _Pragma("unroll") for (int n = 0; n < 2; ++n) _Pragma("unroll") for (int k = 0; k < 2; ++k) dst[n][k] = *(const LAS h16x8*)(lds + PG8_SB(b, h) + boff + n * 2048 + k * 1024); } while (0)
; #define PG8_MMA(ai, bj, At, Bt_) do { __builtin_amdgcn_s_setprio(1); _Pragma("unroll") for (int m = 0; m < 4; ++m) _Pragma("unroll") for (int n = 0; n < 2; ++n) _Pragma("unroll") for (int k = 0; k < 2; ++k) \
;         acc[ai][bj][m][n] = __builtin_amdgcn_mfma_f32_16x16x32_f16(Bt_[n][k], At[m][k], acc[ai][bj][m][n], 0, 0, 0); __builtin_amdgcn_s_setprio(0); } while (0)
; #define PG8_WAIT_V(n) asm volatile("s_waitcnt vmcnt(" #n ")" ::: "memory")
; #define PG8_WAIT_L(n) asm volatile("s_waitcnt lgkmcnt(" #n ")" ::: "memory")
; #define PG8_BAR __builtin_amdgcn_s_barrier()
; #define PG8_SCHED __builtin_amdgcn_sched_barrier(0)
; template <class Epi, class AMap>
; __device__ __forceinline__ void gemm_phase(LAS unsigned char* lds, const AMap am, const int lda, const h16* Bt, const int ldb, const int M, const int N, const int K, const Epi& E) {
;     ...
;             PG8_STAGE(PG8_SB(0, 1), b2 + hstepB, voffB);
;             PG8_WAIT_V(6); PG8_BAR; PG8_MMA(1, 1, At, B1); PG8_BAR;
;             PG8_LDB(B0, 1, 0); PG8_SCHED; PG8_LDA(At, 1, 0); PG8_STAGE(PG8_SA(0, 1), a2 + hstepA, voffA);
;             PG8_WAIT_L(8); PG8_BAR; PG8_WAIT_L(0); PG8_MMA(0, 0, At, B0); PG8_BAR; PG8_SCHED;
;             PG8_LDB(B1, 1, 1); PG8_STAGE(PG8_SB(1, 0), b3, voffB);
;             PG8_BAR; PG8_WAIT_L(0); PG8_MMA(0, 1, At, B1); PG8_BAR;
	s_add_u32 s22, s26, 0x10000
	s_addc_u32 s23, s27, 0
	s_add_i32 s60, s62, s71
	v_lshl_add_u64 v[232:233], s[22:23], 0, v[0:1]
	s_mov_b32 m0, s60
	s_nop 0
	global_load_lds_dwordx4 v[232:233], off
	v_lshl_add_u64 v[232:233], s[22:23], 0, v[150:151]
	s_add_i32 m0, s60, 0x2000
	s_nop 0
	global_load_lds_dwordx4 v[232:233], off
	s_add_i32 s60, 0, 0x18000
	v_add_u32_e32 v234, s60, v175
	ds_read_b128 v[82:85], v234
	ds_read_b128 v[86:89], v234 offset:1024
	ds_read_b128 v[138:141], v234 offset:2048
	ds_read_b128 v[142:145], v234 offset:3072
	s_add_u32 s22, s48, 0x1c0000
	s_addc_u32 s23, s49, 0
	s_mov_b32 m0, s76
	v_lshl_add_u64 v[232:233], s[22:23], 0, v[146:147]
	ds_read_b128 v[156:159], v177 offset:32768
	ds_read_b128 v[160:163], v177 offset:33792
	ds_read_b128 v[164:167], v177 offset:34816
	ds_read_b128 v[168:171], v177 offset:35840
	ds_read_b128 v[178:181], v177 offset:36864
	ds_read_b128 v[182:185], v177 offset:37888
	ds_read_b128 v[186:189], v177 offset:38912
	ds_read_b128 v[190:193], v177 offset:39936
	global_load_lds_dwordx4 v[232:233], off
	v_lshl_add_u64 v[232:233], s[22:23], 0, v[148:149]
	s_mov_b32 m0, s77
	s_nop 0
	global_load_lds_dwordx4 v[232:233], off
	s_waitcnt lgkmcnt(11)
	s_add_i32 s48, 0, 0x1c000
	s_add_i32 s22, s60, s71
	v_add_u32_e32 v214, s48, v175
	v_lshl_add_u64 v[172:173], v[172:173], 0, s[92:93]
	s_mov_b32 m0, s22
	ds_read_b128 v[194:197], v214
	ds_read_b128 v[198:201], v214 offset:1024
	ds_read_b128 v[202:205], v214 offset:2048
	ds_read_b128 v[220:223], v214 offset:3072
	s_waitcnt vmcnt(8) lgkmcnt(0)
	s_barrier
	v_mfma_f32_16x16x32_f16 v[134:137], v[82:85], v[156:159], v[134:137]
	v_mfma_f32_16x16x32_f16 v[130:133], v[138:141], v[156:159], v[130:133]
	v_mfma_f32_16x16x32_f16 v[126:129], v[82:85], v[164:167], v[126:129]
	v_mfma_f32_16x16x32_f16 v[122:125], v[138:141], v[164:167], v[122:125]
	v_mfma_f32_16x16x32_f16 v[118:121], v[82:85], v[178:181], v[118:121]
	v_mfma_f32_16x16x32_f16 v[114:117], v[138:141], v[178:181], v[114:117]
	v_mfma_f32_16x16x32_f16 v[110:113], v[82:85], v[186:189], v[110:113]
	v_mfma_f32_16x16x32_f16 v[106:109], v[138:141], v[186:189], v[106:109]
	v_mfma_f32_16x16x32_f16 v[134:137], v[86:89], v[160:163], v[134:137]
	v_mfma_f32_16x16x32_f16 v[130:133], v[142:145], v[160:163], v[130:133]
	v_mfma_f32_16x16x32_f16 v[126:129], v[86:89], v[168:171], v[126:129]
	v_mfma_f32_16x16x32_f16 v[122:125], v[142:145], v[168:171], v[122:125]
	v_mfma_f32_16x16x32_f16 v[118:121], v[86:89], v[182:185], v[118:121]
	v_mfma_f32_16x16x32_f16 v[114:117], v[142:145], v[182:185], v[114:117]
	v_mfma_f32_16x16x32_f16 v[110:113], v[86:89], v[190:193], v[110:113]
	v_mfma_f32_16x16x32_f16 v[106:109], v[142:145], v[190:193], v[106:109]
	v_mfma_f32_16x16x32_f16 v[62:65], v[194:197], v[156:159], v[62:65]
	v_mfma_f32_16x16x32_f16 v[58:61], v[202:205], v[156:159], v[58:61]
	v_mfma_f32_16x16x32_f16 v[54:57], v[194:197], v[164:167], v[54:57]
	v_mfma_f32_16x16x32_f16 v[50:53], v[202:205], v[164:167], v[50:53]
	v_mfma_f32_16x16x32_f16 v[46:49], v[194:197], v[178:181], v[46:49]
	v_mfma_f32_16x16x32_f16 v[42:45], v[202:205], v[178:181], v[42:45]
	v_mfma_f32_16x16x32_f16 v[38:41], v[194:197], v[186:189], v[38:41]
	v_mfma_f32_16x16x32_f16 v[34:37], v[202:205], v[186:189], v[34:37]
	v_mfma_f32_16x16x32_f16 v[62:65], v[198:201], v[160:163], v[62:65]
	v_mfma_f32_16x16x32_f16 v[58:61], v[220:223], v[160:163], v[58:61]
	v_mfma_f32_16x16x32_f16 v[54:57], v[198:201], v[168:171], v[54:57]
	v_mfma_f32_16x16x32_f16 v[50:53], v[220:223], v[168:171], v[50:53]
	v_mfma_f32_16x16x32_f16 v[46:49], v[198:201], v[182:185], v[46:49]
	v_mfma_f32_16x16x32_f16 v[42:45], v[220:223], v[182:185], v[42:45]
	v_mfma_f32_16x16x32_f16 v[38:41], v[198:201], v[190:193], v[38:41]
	v_mfma_f32_16x16x32_f16 v[34:37], v[220:223], v[190:193], v[34:37]
	s_barrier
; #define PG8_STAGE(bufoff, gbase, voff) do { _Pragma("unroll") for (int _i = 0; _i < 2; ++_i) \
;         __builtin_amdgcn_global_load_lds((const unsigned*)((const char*)(gbase) + (voff)[_i]), (LAS unsigned*)(lds + (bufoff) + ldsw + _i * 8192), 16, 0, 0); } while (0)
; #define PG8_LDA(dst, b, h) do { _Pragma("unroll") for (int m = 0; m < 4; ++m) _Pragma("unroll") for (int k = 0; k < 2; ++k) dst[m][k] = *(const LAS h16x8*)(lds + PG8_SA(b, h) + aoff + m * 2048 + k * 1024); } while (0)
; #define PG8_MMA(ai, bj, At, Bt_) do { __builtin_amdgcn_s_setprio(1); _Pragma("unroll") for (int m = 0; m < 4; ++m) _Pragma("unroll") for (int n = 0; n < 2; ++n) _Pragma("unroll") for (int k = 0; k < 2; ++k) \
;         acc[ai][bj][m][n] = __builtin_amdgcn_mfma_f32_16x16x32_f16(Bt_[n][k], At[m][k], acc[ai][bj][m][n], 0, 0, 0); __builtin_amdgcn_s_setprio(0); } while (0)
; #define PG8_WAIT_V(n) asm volatile("s_waitcnt vmcnt(" #n ")" ::: "memory")
; #define PG8_WAIT_L(n) asm volatile("s_waitcnt lgkmcnt(" #n ")" ::: "memory")
; #define PG8_BAR __builtin_amdgcn_s_barrier()
; #define PG8_SCHED __builtin_amdgcn_sched_barrier(0)
; template <class Epi, class AMap>
; __device__ __forceinline__ void gemm_phase(LAS unsigned char* lds, const AMap am, const int lda, const h16* Bt, const int ldb, const int M, const int N, const int K, const Epi& E) {
;     ...
;             PG8_LDA(At, 1, 1); PG8_STAGE(PG8_SA(1, 0), a3, voffA);
;             PG8_BAR; PG8_WAIT_L(0); PG8_MMA(1, 0, At, B0); PG8_BAR; PG8_SCHED;
;             PG8_STAGE(PG8_SB(1, 1), b3 + hstepB, voffB);
;             PG8_WAIT_V(6); PG8_BAR; PG8_MMA(1, 1, At, B1); PG8_BAR;
;         }
;         E(acc, cur, wr, wc, fr, fq);
;         if (!has_next) break;
	global_load_lds_dwordx4 v[172:173], off
	v_lshl_add_u64 v[172:173], v[206:207], 0, s[92:93]
	s_add_i32 m0, s22, 0x2000
	s_nop 0
	global_load_lds_dwordx4 v[172:173], off
	s_mov_b32 m0, s79
	v_lshl_add_u64 v[172:173], v[212:213], 0, s[92:93]
	ds_read_b128 v[156:159], v177 offset:49152
	ds_read_b128 v[160:163], v177 offset:50176
	ds_read_b128 v[164:167], v177 offset:51200
	ds_read_b128 v[168:171], v177 offset:52224
	ds_read_b128 v[178:181], v177 offset:53248
	ds_read_b128 v[182:185], v177 offset:54272
	ds_read_b128 v[186:189], v177 offset:55296
	ds_read_b128 v[190:193], v177 offset:56320
	global_load_lds_dwordx4 v[172:173], off
	v_lshl_add_u64 v[172:173], v[224:225], 0, s[92:93]
	s_mov_b32 m0, s80
	s_nop 0
	global_load_lds_dwordx4 v[172:173], off
	s_add_u32 s22, s26, 0x10080
	s_addc_u32 s23, s27, 0
	s_add_i32 s26, s48, s71
	v_lshl_add_u64 v[232:233], s[22:23], 0, v[0:1]
	s_mov_b32 m0, s26
	s_nop 0
	global_load_lds_dwordx4 v[232:233], off
	v_lshl_add_u64 v[232:233], s[22:23], 0, v[150:151]
	s_add_i32 m0, s26, 0x2000
	s_nop 0
	global_load_lds_dwordx4 v[232:233], off
	s_add_u32 s29, s29, 0x100
	s_addc_u32 s45, s45, 0
	s_cmp_ge_i32 s51, s24
	s_mov_b64 s[22:23], s[0:1]
	s_mov_b32 s26, s51
	s_waitcnt vmcnt(8) lgkmcnt(0)
	s_barrier
	v_mfma_f32_16x16x32_f16 v[102:105], v[82:85], v[156:159], v[102:105]
	v_mfma_f32_16x16x32_f16 v[98:101], v[138:141], v[156:159], v[98:101]
	v_mfma_f32_16x16x32_f16 v[94:97], v[82:85], v[164:167], v[94:97]
	v_mfma_f32_16x16x32_f16 v[90:93], v[138:141], v[164:167], v[90:93]
	v_mfma_f32_16x16x32_f16 v[78:81], v[82:85], v[178:181], v[78:81]
	v_mfma_f32_16x16x32_f16 v[74:77], v[138:141], v[178:181], v[74:77]
	v_mfma_f32_16x16x32_f16 v[70:73], v[82:85], v[186:189], v[70:73]
	v_mfma_f32_16x16x32_f16 v[66:69], v[138:141], v[186:189], v[66:69]
	v_mfma_f32_16x16x32_f16 v[102:105], v[86:89], v[160:163], v[102:105]
	v_mfma_f32_16x16x32_f16 v[98:101], v[142:145], v[160:163], v[98:101]
	v_mfma_f32_16x16x32_f16 v[94:97], v[86:89], v[168:171], v[94:97]
	v_mfma_f32_16x16x32_f16 v[90:93], v[142:145], v[168:171], v[90:93]
	v_mfma_f32_16x16x32_f16 v[78:81], v[86:89], v[182:185], v[78:81]
	v_mfma_f32_16x16x32_f16 v[74:77], v[142:145], v[182:185], v[74:77]
	v_mfma_f32_16x16x32_f16 v[70:73], v[86:89], v[190:193], v[70:73]
	v_mfma_f32_16x16x32_f16 v[66:69], v[142:145], v[190:193], v[66:69]
	v_mfma_f32_16x16x32_f16 v[30:33], v[194:197], v[156:159], v[30:33]
	v_mfma_f32_16x16x32_f16 v[26:29], v[202:205], v[156:159], v[26:29]
	v_mfma_f32_16x16x32_f16 v[22:25], v[194:197], v[164:167], v[22:25]
	v_mfma_f32_16x16x32_f16 v[18:21], v[202:205], v[164:167], v[18:21]
	v_mfma_f32_16x16x32_f16 v[14:17], v[194:197], v[178:181], v[14:17]
	v_mfma_f32_16x16x32_f16 v[10:13], v[202:205], v[178:181], v[10:13]
	v_mfma_f32_16x16x32_f16 v[6:9], v[194:197], v[186:189], v[6:9]
	v_mfma_f32_16x16x32_f16 v[2:5], v[202:205], v[186:189], v[2:5]
	v_mfma_f32_16x16x32_f16 v[30:33], v[198:201], v[160:163], v[30:33]
	v_mfma_f32_16x16x32_f16 v[26:29], v[220:223], v[160:163], v[26:29]
	v_mfma_f32_16x16x32_f16 v[22:25], v[198:201], v[168:171], v[22:25]
	v_mfma_f32_16x16x32_f16 v[18:21], v[220:223], v[168:171], v[18:21]
	v_mfma_f32_16x16x32_f16 v[14:17], v[198:201], v[182:185], v[14:17]
	v_mfma_f32_16x16x32_f16 v[10:13], v[220:223], v[182:185], v[10:13]
	v_mfma_f32_16x16x32_f16 v[6:9], v[198:201], v[190:193], v[6:9]
	v_mfma_f32_16x16x32_f16 v[2:5], v[220:223], v[190:193], v[2:5]
	s_barrier
	s_cbranch_scc0 .LBB0_692
	s_branch .LBB0_681
